# GEMM K-loop MFMA segments padded (s_nop in the load segment) so every 8-byte MFMA starts on an 8-byte boundary
# speedup vs baseline: 1.0019x; 1.0019x over previous
; #define PG8_WAIT_V(n) asm volatile("s_waitcnt vmcnt(" #n ")" ::: "memory")
; #define PG8_WAIT_L(n) asm volatile("s_waitcnt lgkmcnt(" #n ")" ::: "memory")
; #define PG8_BAR __builtin_amdgcn_s_barrier()
; #define PG8_SCHED __builtin_amdgcn_sched_barrier(0)
; template <class Epi, class Sched, bool ALIGN_EPI = false, bool SP2 = false, bool F8 = false>
; __device__ __forceinline__ void gemm_phase(PG8_LAS unsigned char* lds, const Gemm g, const Sched& S, const Epi& E) {
;     ...
;         for (int t = 0; t < nt; t += 2) {
;             const bool last = (t == nt - 2);
;             const char* a1 = cA + (size_t)(t + 1) * kstep;
;             const char* a2 = last ? nA : cA + (size_t)(t + 2) * kstep; const char* b2 = last ? nB : cB + (size_t)(t + 2) * kstep;
;             const char* a3 = a2 + kstep; const char* b3 = b2 + kstep;
;             if (last && has_next) S.a_ready(nxt);
;             if constexpr (SP2) {
;             PG8_LDB(B0, 0, 0); PG8_LDB(B1, 0, 1); PG8_SCHED; PG8_LDA(At, 0, 0); PG8_STAGE(PG8_SA(1, 1), a1 + hstep, voffA);
;             PG8_WAIT_V(8); PG8_WAIT_L(0); PG8_BAR; PG8_MMA(0, 0, At, B0); PG8_MMA(0, 1, At, B1); PG8_BAR; PG8_SCHED;
;             PG8_LDA(At, 0, 1); PG8_STAGE(PG8_SB(0, 0), b2, voffB); PG8_STAGE(PG8_SB(0, 1), b2 + hstep, voffB); PG8_STAGE(PG8_SA(0, 0), a2, voffA);
;             PG8_WAIT_V(8); PG8_WAIT_L(0); PG8_BAR; PG8_MMA(1, 0, At, B0); PG8_MMA(1, 1, At, B1); PG8_BAR; PG8_SCHED;
;             PG8_LDB(B0, 1, 0); PG8_LDB(B1, 1, 1); PG8_SCHED; PG8_LDA(At, 1, 0); PG8_STAGE(PG8_SA(0, 1), a2 + hstep, voffA);
;             PG8_WAIT_V(8); PG8_WAIT_L(0); PG8_BAR; PG8_MMA(0, 0, At, B0); PG8_MMA(0, 1, At, B1); PG8_BAR; PG8_SCHED;
;             PG8_LDA(At, 1, 1); PG8_STAGE(PG8_SB(1, 0), b3, voffB); PG8_STAGE(PG8_SB(1, 1), b3 + hstep, voffB); PG8_STAGE(PG8_SA(1, 0), a3, voffA);
;             PG8_WAIT_V(8); PG8_WAIT_L(0); PG8_BAR; PG8_MMA(1, 0, At, B0); PG8_MMA(1, 1, At, B1); PG8_BAR; PG8_SCHED;
.LBB0_297:
	s_add_u32 s18, s16, 0x4000
	s_addc_u32 s19, s17, 0
	s_cmp_eq_u32 s63, 28
	s_cselect_b32 s30, s59, s18
	s_cselect_b32 s31, s11, s19
	s_cselect_b32 s22, s60, s61
	s_cselect_b32 s23, s9, s62
	s_add_u32 s20, s30, 0x2000
	s_addc_u32 s21, s31, 0
	s_add_i32 s65, 0, 0x10000
	v_add_u32_e32 v145, s65, v153
	s_add_i32 s67, 0, 0x14000
	ds_read_b128 v[156:159], v145
	ds_read_b128 v[160:163], v145 offset:1024
	ds_read_b128 v[164:167], v145 offset:2048
	ds_read_b128 v[168:171], v145 offset:3072
	v_add_u32_e32 v145, s67, v153
	ds_read_b128 v[184:187], v145
	ds_read_b128 v[188:191], v145 offset:1024
	ds_read_b128 v[192:195], v145 offset:2048
	ds_read_b128 v[196:199], v145 offset:3072
	s_add_u32 s46, s16, 0x2000
	s_addc_u32 s47, s17, 0
	s_mov_b32 m0, s50
	ds_read_b128 v[200:203], v155
	ds_read_b128 v[204:207], v155 offset:1024
	ds_read_b128 v[208:211], v155 offset:2048
	ds_read_b128 v[228:231], v155 offset:3072
	ds_read_b128 v[232:235], v155 offset:4096
	ds_read_b128 v[236:239], v155 offset:5120
	ds_read_b128 v[240:243], v155 offset:6144
	ds_read_b128 v[244:247], v155 offset:7168
	global_load_lds_dwordx4 v138, s[46:47]
	s_mov_b32 m0, s52
	s_nop 0
	global_load_lds_dwordx4 v134, s[46:47]
	s_add_i32 m0, s40, 0xc000
	s_nop 0
	global_load_lds_dwordx4 v140, s[16:17]
	s_add_i32 m0, s40, 0xe000
	s_nop 0
	global_load_lds_dwordx4 v142, s[16:17]
	s_waitcnt vmcnt(8)
	s_waitcnt lgkmcnt(0)
	s_nop 0
	s_barrier
	s_setprio 1
	s_waitcnt lgkmcnt(0)
	v_mfma_f32_16x16x32_bf16 v[128:131], v[156:159], v[200:203], v[128:131]
	v_mfma_f32_16x16x32_bf16 v[124:127], v[164:167], v[200:203], v[124:127]
	v_mfma_f32_16x16x32_bf16 v[112:115], v[156:159], v[208:211], v[112:115]
	v_mfma_f32_16x16x32_bf16 v[108:111], v[164:167], v[208:211], v[108:111]
	v_mfma_f32_16x16x32_bf16 v[96:99], v[156:159], v[232:235], v[96:99]
	v_mfma_f32_16x16x32_bf16 v[92:95], v[164:167], v[232:235], v[92:95]
	v_mfma_f32_16x16x32_bf16 v[80:83], v[156:159], v[240:243], v[80:83]
	v_mfma_f32_16x16x32_bf16 v[76:79], v[164:167], v[240:243], v[76:79]
	v_mfma_f32_16x16x32_bf16 v[128:131], v[160:163], v[204:207], v[128:131]
	v_mfma_f32_16x16x32_bf16 v[124:127], v[168:171], v[204:207], v[124:127]
	v_mfma_f32_16x16x32_bf16 v[112:115], v[160:163], v[228:231], v[112:115]
	v_mfma_f32_16x16x32_bf16 v[108:111], v[168:171], v[228:231], v[108:111]
	v_mfma_f32_16x16x32_bf16 v[96:99], v[160:163], v[236:239], v[96:99]
	v_mfma_f32_16x16x32_bf16 v[92:95], v[168:171], v[236:239], v[92:95]
	v_mfma_f32_16x16x32_bf16 v[80:83], v[160:163], v[244:247], v[80:83]
	v_mfma_f32_16x16x32_bf16 v[76:79], v[168:171], v[244:247], v[76:79]
	s_setprio 0
	s_setprio 1
	v_mfma_f32_16x16x32_bf16 v[120:123], v[184:187], v[200:203], v[120:123]
	v_mfma_f32_16x16x32_bf16 v[116:119], v[192:195], v[200:203], v[116:119]
	v_mfma_f32_16x16x32_bf16 v[104:107], v[184:187], v[208:211], v[104:107]
	v_mfma_f32_16x16x32_bf16 v[100:103], v[192:195], v[208:211], v[100:103]
	v_mfma_f32_16x16x32_bf16 v[88:91], v[184:187], v[232:235], v[88:91]
	v_mfma_f32_16x16x32_bf16 v[84:87], v[192:195], v[232:235], v[84:87]
	v_mfma_f32_16x16x32_bf16 v[72:75], v[184:187], v[240:243], v[72:75]
	v_mfma_f32_16x16x32_bf16 v[68:71], v[192:195], v[240:243], v[68:71]
	v_mfma_f32_16x16x32_bf16 v[120:123], v[188:191], v[204:207], v[120:123]
	v_mfma_f32_16x16x32_bf16 v[116:119], v[196:199], v[204:207], v[116:119]
	v_mfma_f32_16x16x32_bf16 v[104:107], v[188:191], v[228:231], v[104:107]
	v_mfma_f32_16x16x32_bf16 v[100:103], v[196:199], v[228:231], v[100:103]
	v_mfma_f32_16x16x32_bf16 v[88:91], v[188:191], v[236:239], v[88:91]
	v_mfma_f32_16x16x32_bf16 v[84:87], v[196:199], v[236:239], v[84:87]
	v_mfma_f32_16x16x32_bf16 v[72:75], v[188:191], v[244:247], v[72:75]
	v_mfma_f32_16x16x32_bf16 v[68:71], v[196:199], v[244:247], v[68:71]
	s_setprio 0
	s_barrier
	s_add_i32 s16, s65, s26
	s_mov_b32 m0, s16
	ds_read_b128 v[200:203], v155 offset:16384
	ds_read_b128 v[204:207], v155 offset:17408
	ds_read_b128 v[208:211], v155 offset:18432
	ds_read_b128 v[228:231], v155 offset:19456
	ds_read_b128 v[232:235], v155 offset:20480
	ds_read_b128 v[236:239], v155 offset:21504
	ds_read_b128 v[240:243], v155 offset:22528
	ds_read_b128 v[244:247], v155 offset:23552
	global_load_lds_dwordx4 v136, s[22:23]
	s_add_i32 m0, s16, 0x2000
	s_add_u32 s16, s22, 0x80000
	s_addc_u32 s17, s23, 0
	s_add_i32 s65, s67, s26
	global_load_lds_dwordx4 v132, s[22:23]
	s_mov_b32 m0, s65
	s_nop 0
	global_load_lds_dwordx4 v136, s[16:17]
	s_add_i32 m0, s65, 0x2000
	s_nop 0
	global_load_lds_dwordx4 v132, s[16:17]
	s_waitcnt vmcnt(6)
	s_waitcnt lgkmcnt(0)
	s_barrier
; #define PG8_WAIT_V(n) asm volatile("s_waitcnt vmcnt(" #n ")" ::: "memory")
; #define PG8_WAIT_L(n) asm volatile("s_waitcnt lgkmcnt(" #n ")" ::: "memory")
; #define PG8_BAR __builtin_amdgcn_s_barrier()
; #define PG8_SCHED __builtin_amdgcn_sched_barrier(0)
; template <class Epi, class Sched, bool ALIGN_EPI = false, bool SP2 = false, bool F8 = false>
; __device__ __forceinline__ void gemm_phase(PG8_LAS unsigned char* lds, const Gemm g, const Sched& S, const Epi& E) {
;     ...
;             PG8_LDB(B0, 0, 0); PG8_LDB(B1, 0, 1); PG8_SCHED; PG8_LDA(At, 0, 0); PG8_STAGE(PG8_SA(1, 1), a1 + hstep, voffA);
;             PG8_WAIT_V(8); PG8_WAIT_L(0); PG8_BAR; PG8_MMA(0, 0, At, B0); PG8_MMA(0, 1, At, B1); PG8_BAR; PG8_SCHED;
;             PG8_LDA(At, 0, 1); PG8_STAGE(PG8_SB(0, 0), b2, voffB); PG8_STAGE(PG8_SB(0, 1), b2 + hstep, voffB); PG8_STAGE(PG8_SA(0, 0), a2, voffA);
;             PG8_WAIT_V(8); PG8_WAIT_L(0); PG8_BAR; PG8_MMA(1, 0, At, B0); PG8_MMA(1, 1, At, B1); PG8_BAR; PG8_SCHED;
;             PG8_LDB(B0, 1, 0); PG8_LDB(B1, 1, 1); PG8_SCHED; PG8_LDA(At, 1, 0); PG8_STAGE(PG8_SA(0, 1), a2 + hstep, voffA);
;             PG8_WAIT_V(8); PG8_WAIT_L(0); PG8_BAR; PG8_MMA(0, 0, At, B0); PG8_MMA(0, 1, At, B1); PG8_BAR; PG8_SCHED;
;             PG8_LDA(At, 1, 1); PG8_STAGE(PG8_SB(1, 0), b3, voffB); PG8_STAGE(PG8_SB(1, 1), b3 + hstep, voffB); PG8_STAGE(PG8_SA(1, 0), a3, voffA);
;             PG8_WAIT_V(8); PG8_WAIT_L(0); PG8_BAR; PG8_MMA(1, 0, At, B0); PG8_MMA(1, 1, At, B1); PG8_BAR; PG8_SCHED;
	s_setprio 1
	s_waitcnt lgkmcnt(0)
	v_mfma_f32_16x16x32_bf16 v[64:67], v[156:159], v[200:203], v[64:67]
	v_mfma_f32_16x16x32_bf16 v[60:63], v[164:167], v[200:203], v[60:63]
	v_mfma_f32_16x16x32_bf16 v[48:51], v[156:159], v[208:211], v[48:51]
	v_mfma_f32_16x16x32_bf16 v[44:47], v[164:167], v[208:211], v[44:47]
	v_mfma_f32_16x16x32_bf16 v[32:35], v[156:159], v[232:235], v[32:35]
	v_mfma_f32_16x16x32_bf16 v[28:31], v[164:167], v[232:235], v[28:31]
	v_mfma_f32_16x16x32_bf16 v[16:19], v[156:159], v[240:243], v[16:19]
	v_mfma_f32_16x16x32_bf16 v[12:15], v[164:167], v[240:243], v[12:15]
	v_mfma_f32_16x16x32_bf16 v[64:67], v[160:163], v[204:207], v[64:67]
	v_mfma_f32_16x16x32_bf16 v[60:63], v[168:171], v[204:207], v[60:63]
	v_mfma_f32_16x16x32_bf16 v[48:51], v[160:163], v[228:231], v[48:51]
	v_mfma_f32_16x16x32_bf16 v[44:47], v[168:171], v[228:231], v[44:47]
	v_mfma_f32_16x16x32_bf16 v[32:35], v[160:163], v[236:239], v[32:35]
	v_mfma_f32_16x16x32_bf16 v[28:31], v[168:171], v[236:239], v[28:31]
	v_mfma_f32_16x16x32_bf16 v[16:19], v[160:163], v[244:247], v[16:19]
	v_mfma_f32_16x16x32_bf16 v[12:15], v[168:171], v[244:247], v[12:15]
	s_setprio 0
	s_setprio 1
	v_mfma_f32_16x16x32_bf16 v[56:59], v[184:187], v[200:203], v[56:59]
	v_mfma_f32_16x16x32_bf16 v[52:55], v[192:195], v[200:203], v[52:55]
	v_mfma_f32_16x16x32_bf16 v[40:43], v[184:187], v[208:211], v[40:43]
	v_mfma_f32_16x16x32_bf16 v[36:39], v[192:195], v[208:211], v[36:39]
	v_mfma_f32_16x16x32_bf16 v[24:27], v[184:187], v[232:235], v[24:27]
	v_mfma_f32_16x16x32_bf16 v[20:23], v[192:195], v[232:235], v[20:23]
	v_mfma_f32_16x16x32_bf16 v[8:11], v[184:187], v[240:243], v[8:11]
	v_mfma_f32_16x16x32_bf16 v[4:7], v[192:195], v[240:243], v[4:7]
	v_mfma_f32_16x16x32_bf16 v[56:59], v[188:191], v[204:207], v[56:59]
	v_mfma_f32_16x16x32_bf16 v[52:55], v[196:199], v[204:207], v[52:55]
	v_mfma_f32_16x16x32_bf16 v[40:43], v[188:191], v[228:231], v[40:43]
	v_mfma_f32_16x16x32_bf16 v[36:39], v[196:199], v[228:231], v[36:39]
	v_mfma_f32_16x16x32_bf16 v[24:27], v[188:191], v[236:239], v[24:27]
	v_mfma_f32_16x16x32_bf16 v[20:23], v[196:199], v[236:239], v[20:23]
	v_mfma_f32_16x16x32_bf16 v[8:11], v[188:191], v[244:247], v[8:11]
	v_mfma_f32_16x16x32_bf16 v[4:7], v[196:199], v[244:247], v[4:7]
	s_setprio 0
	s_barrier
	s_add_i32 s65, 0, 0x18000
	v_add_u32_e32 v145, s65, v153
	s_add_i32 s67, 0, 0x1c000
	ds_read_b128 v[156:159], v145
	ds_read_b128 v[160:163], v145 offset:1024
	ds_read_b128 v[164:167], v145 offset:2048
	ds_read_b128 v[168:171], v145 offset:3072
	v_add_u32_e32 v145, s67, v153
	ds_read_b128 v[184:187], v145
	ds_read_b128 v[188:191], v145 offset:1024
	ds_read_b128 v[192:195], v145 offset:2048
	ds_read_b128 v[196:199], v145 offset:3072
	s_add_u32 s16, s30, 0x80000
	s_addc_u32 s17, s31, 0
	s_mov_b32 m0, s40
	ds_read_b128 v[200:203], v155 offset:32768
	ds_read_b128 v[204:207], v155 offset:33792
	ds_read_b128 v[208:211], v155 offset:34816
	ds_read_b128 v[228:231], v155 offset:35840
	ds_read_b128 v[232:235], v155 offset:36864
	ds_read_b128 v[236:239], v155 offset:37888
	ds_read_b128 v[240:243], v155 offset:38912
	ds_read_b128 v[244:247], v155 offset:39936
	global_load_lds_dwordx4 v138, s[30:31]
	s_mov_b32 m0, s41
	s_nop 0
	global_load_lds_dwordx4 v134, s[30:31]
	s_mov_b32 m0, s42
	s_nop 0
	global_load_lds_dwordx4 v138, s[16:17]
	s_mov_b32 m0, s45
	s_nop 0
	global_load_lds_dwordx4 v134, s[16:17]
	s_waitcnt vmcnt(8)
	s_waitcnt lgkmcnt(0)
	s_nop 0
	s_barrier
; #define PG8_WAIT_V(n) asm volatile("s_waitcnt vmcnt(" #n ")" ::: "memory")
; #define PG8_WAIT_L(n) asm volatile("s_waitcnt lgkmcnt(" #n ")" ::: "memory")
; #define PG8_BAR __builtin_amdgcn_s_barrier()
; #define PG8_SCHED __builtin_amdgcn_sched_barrier(0)
; template <class Epi, class Sched, bool ALIGN_EPI = false, bool SP2 = false, bool F8 = false>
; __device__ __forceinline__ void gemm_phase(PG8_LAS unsigned char* lds, const Gemm g, const Sched& S, const Epi& E) {
;     ...
;             PG8_LDB(B0, 0, 0); PG8_LDB(B1, 0, 1); PG8_SCHED; PG8_LDA(At, 0, 0); PG8_STAGE(PG8_SA(1, 1), a1 + hstep, voffA);
;             PG8_WAIT_V(8); PG8_WAIT_L(0); PG8_BAR; PG8_MMA(0, 0, At, B0); PG8_MMA(0, 1, At, B1); PG8_BAR; PG8_SCHED;
;             PG8_LDA(At, 0, 1); PG8_STAGE(PG8_SB(0, 0), b2, voffB); PG8_STAGE(PG8_SB(0, 1), b2 + hstep, voffB); PG8_STAGE(PG8_SA(0, 0), a2, voffA);
;             PG8_WAIT_V(8); PG8_WAIT_L(0); PG8_BAR; PG8_MMA(1, 0, At, B0); PG8_MMA(1, 1, At, B1); PG8_BAR; PG8_SCHED;
;             PG8_LDB(B0, 1, 0); PG8_LDB(B1, 1, 1); PG8_SCHED; PG8_LDA(At, 1, 0); PG8_STAGE(PG8_SA(0, 1), a2 + hstep, voffA);
;             PG8_WAIT_V(8); PG8_WAIT_L(0); PG8_BAR; PG8_MMA(0, 0, At, B0); PG8_MMA(0, 1, At, B1); PG8_BAR; PG8_SCHED;
;             PG8_LDA(At, 1, 1); PG8_STAGE(PG8_SB(1, 0), b3, voffB); PG8_STAGE(PG8_SB(1, 1), b3 + hstep, voffB); PG8_STAGE(PG8_SA(1, 0), a3, voffA);
;             PG8_WAIT_V(8); PG8_WAIT_L(0); PG8_BAR; PG8_MMA(1, 0, At, B0); PG8_MMA(1, 1, At, B1); PG8_BAR; PG8_SCHED;
	s_setprio 1
	s_waitcnt lgkmcnt(0)
	v_mfma_f32_16x16x32_bf16 v[128:131], v[156:159], v[200:203], v[128:131]
	v_mfma_f32_16x16x32_bf16 v[124:127], v[164:167], v[200:203], v[124:127]
	v_mfma_f32_16x16x32_bf16 v[112:115], v[156:159], v[208:211], v[112:115]
	v_mfma_f32_16x16x32_bf16 v[108:111], v[164:167], v[208:211], v[108:111]
	v_mfma_f32_16x16x32_bf16 v[96:99], v[156:159], v[232:235], v[96:99]
	v_mfma_f32_16x16x32_bf16 v[92:95], v[164:167], v[232:235], v[92:95]
	v_mfma_f32_16x16x32_bf16 v[80:83], v[156:159], v[240:243], v[80:83]
	v_mfma_f32_16x16x32_bf16 v[76:79], v[164:167], v[240:243], v[76:79]
	v_mfma_f32_16x16x32_bf16 v[128:131], v[160:163], v[204:207], v[128:131]
	v_mfma_f32_16x16x32_bf16 v[124:127], v[168:171], v[204:207], v[124:127]
	v_mfma_f32_16x16x32_bf16 v[112:115], v[160:163], v[228:231], v[112:115]
	v_mfma_f32_16x16x32_bf16 v[108:111], v[168:171], v[228:231], v[108:111]
	v_mfma_f32_16x16x32_bf16 v[96:99], v[160:163], v[236:239], v[96:99]
	v_mfma_f32_16x16x32_bf16 v[92:95], v[168:171], v[236:239], v[92:95]
	v_mfma_f32_16x16x32_bf16 v[80:83], v[160:163], v[244:247], v[80:83]
	v_mfma_f32_16x16x32_bf16 v[76:79], v[168:171], v[244:247], v[76:79]
	s_setprio 0
	s_setprio 1
	v_mfma_f32_16x16x32_bf16 v[120:123], v[184:187], v[200:203], v[120:123]
	v_mfma_f32_16x16x32_bf16 v[116:119], v[192:195], v[200:203], v[116:119]
	v_mfma_f32_16x16x32_bf16 v[104:107], v[184:187], v[208:211], v[104:107]
	v_mfma_f32_16x16x32_bf16 v[100:103], v[192:195], v[208:211], v[100:103]
	v_mfma_f32_16x16x32_bf16 v[88:91], v[184:187], v[232:235], v[88:91]
	v_mfma_f32_16x16x32_bf16 v[84:87], v[192:195], v[232:235], v[84:87]
	v_mfma_f32_16x16x32_bf16 v[72:75], v[184:187], v[240:243], v[72:75]
	v_mfma_f32_16x16x32_bf16 v[68:71], v[192:195], v[240:243], v[68:71]
	v_mfma_f32_16x16x32_bf16 v[120:123], v[188:191], v[204:207], v[120:123]
	v_mfma_f32_16x16x32_bf16 v[116:119], v[196:199], v[204:207], v[116:119]
	v_mfma_f32_16x16x32_bf16 v[104:107], v[188:191], v[228:231], v[104:107]
	v_mfma_f32_16x16x32_bf16 v[100:103], v[196:199], v[228:231], v[100:103]
	v_mfma_f32_16x16x32_bf16 v[88:91], v[188:191], v[236:239], v[88:91]
	v_mfma_f32_16x16x32_bf16 v[84:87], v[196:199], v[236:239], v[84:87]
	v_mfma_f32_16x16x32_bf16 v[72:75], v[188:191], v[244:247], v[72:75]
	v_mfma_f32_16x16x32_bf16 v[68:71], v[196:199], v[244:247], v[68:71]
	s_setprio 0
	s_barrier
	s_add_u32 s16, s22, 0x2000
	s_addc_u32 s17, s23, 0
	s_add_i32 s30, s65, s26
	s_mov_b32 m0, s30
	ds_read_b128 v[200:203], v155 offset:49152
	ds_read_b128 v[204:207], v155 offset:50176
	ds_read_b128 v[208:211], v155 offset:51200
	ds_read_b128 v[228:231], v155 offset:52224
	ds_read_b128 v[232:235], v155 offset:53248
	ds_read_b128 v[236:239], v155 offset:54272
	ds_read_b128 v[240:243], v155 offset:55296
	ds_read_b128 v[244:247], v155 offset:56320
	global_load_lds_dwordx4 v136, s[16:17]
	s_add_i32 m0, s30, 0x2000
	s_nop 0
	global_load_lds_dwordx4 v132, s[16:17]
	s_add_u32 s16, s22, 0x82000
	s_addc_u32 s17, s23, 0
	s_add_i32 s22, s67, s26
	s_mov_b32 m0, s22
	s_nop 0
	global_load_lds_dwordx4 v136, s[16:17]
	s_add_i32 m0, s22, 0x2000
	s_nop 0
	global_load_lds_dwordx4 v132, s[16:17]
	s_waitcnt vmcnt(6)
	s_waitcnt lgkmcnt(0)
	s_barrier
	s_setprio 1
	s_waitcnt lgkmcnt(0)
	v_mfma_f32_16x16x32_bf16 v[64:67], v[156:159], v[200:203], v[64:67]
	v_mfma_f32_16x16x32_bf16 v[60:63], v[164:167], v[200:203], v[60:63]
	v_mfma_f32_16x16x32_bf16 v[48:51], v[156:159], v[208:211], v[48:51]
	v_mfma_f32_16x16x32_bf16 v[44:47], v[164:167], v[208:211], v[44:47]
	v_mfma_f32_16x16x32_bf16 v[32:35], v[156:159], v[232:235], v[32:35]
	v_mfma_f32_16x16x32_bf16 v[28:31], v[164:167], v[232:235], v[28:31]
	v_mfma_f32_16x16x32_bf16 v[16:19], v[156:159], v[240:243], v[16:19]
	v_mfma_f32_16x16x32_bf16 v[12:15], v[164:167], v[240:243], v[12:15]
	v_mfma_f32_16x16x32_bf16 v[64:67], v[160:163], v[204:207], v[64:67]
	v_mfma_f32_16x16x32_bf16 v[60:63], v[168:171], v[204:207], v[60:63]
	v_mfma_f32_16x16x32_bf16 v[48:51], v[160:163], v[228:231], v[48:51]
	v_mfma_f32_16x16x32_bf16 v[44:47], v[168:171], v[228:231], v[44:47]
	v_mfma_f32_16x16x32_bf16 v[32:35], v[160:163], v[236:239], v[32:35]
	v_mfma_f32_16x16x32_bf16 v[28:31], v[168:171], v[236:239], v[28:31]
	v_mfma_f32_16x16x32_bf16 v[16:19], v[160:163], v[244:247], v[16:19]
	v_mfma_f32_16x16x32_bf16 v[12:15], v[168:171], v[244:247], v[12:15]
	s_setprio 0
	s_setprio 1
	v_mfma_f32_16x16x32_bf16 v[56:59], v[184:187], v[200:203], v[56:59]
	v_mfma_f32_16x16x32_bf16 v[52:55], v[192:195], v[200:203], v[52:55]
	v_mfma_f32_16x16x32_bf16 v[40:43], v[184:187], v[208:211], v[40:43]
	v_mfma_f32_16x16x32_bf16 v[36:39], v[192:195], v[208:211], v[36:39]
	v_mfma_f32_16x16x32_bf16 v[24:27], v[184:187], v[232:235], v[24:27]
	v_mfma_f32_16x16x32_bf16 v[20:23], v[192:195], v[232:235], v[20:23]
	v_mfma_f32_16x16x32_bf16 v[8:11], v[184:187], v[240:243], v[8:11]
	v_mfma_f32_16x16x32_bf16 v[4:7], v[192:195], v[240:243], v[4:7]
	v_mfma_f32_16x16x32_bf16 v[56:59], v[188:191], v[204:207], v[56:59]
	v_mfma_f32_16x16x32_bf16 v[52:55], v[196:199], v[204:207], v[52:55]
	v_mfma_f32_16x16x32_bf16 v[40:43], v[188:191], v[228:231], v[40:43]
	v_mfma_f32_16x16x32_bf16 v[36:39], v[196:199], v[228:231], v[36:39]
	v_mfma_f32_16x16x32_bf16 v[24:27], v[188:191], v[236:239], v[24:27]
	v_mfma_f32_16x16x32_bf16 v[20:23], v[196:199], v[236:239], v[20:23]
	v_mfma_f32_16x16x32_bf16 v[8:11], v[188:191], v[244:247], v[8:11]
	v_mfma_f32_16x16x32_bf16 v[4:7], v[196:199], v[244:247], v[4:7]
	s_setprio 0
	s_barrier
	s_add_i32 s63, s63, 2
	s_add_u32 s61, s61, 0x4000
	s_addc_u32 s62, s62, 0
	s_cmp_gt_u32 s63, 29
	s_mov_b64 s[16:17], s[18:19]
	s_cbranch_scc0 .LBB0_297
	s_and_b64 vcc, exec, s[6:7]
	s_cbranch_vccz .LBB0_300
	s_barrier

; #define PG8_WAIT_V(n) asm volatile("s_waitcnt vmcnt(" #n ")" ::: "memory")
; #define PG8_WAIT_L(n) asm volatile("s_waitcnt lgkmcnt(" #n ")" ::: "memory")
; #define PG8_BAR __builtin_amdgcn_s_barrier()
; #define PG8_SCHED __builtin_amdgcn_sched_barrier(0)
; template <class Epi, class Sched, bool ALIGN_EPI = false, bool SP2 = false, bool F8 = false>
; __device__ __forceinline__ void gemm_phase(PG8_LAS unsigned char* lds, const Gemm g, const Sched& S, const Epi& E) {
;     ...
;             PG8_LDB(B0, 0, 0); PG8_LDB(B1, 0, 1); PG8_SCHED; PG8_LDA(At, 0, 0); PG8_STAGE(PG8_SA(1, 1), a1 + hstep, voffA);
;             PG8_WAIT_V(8); PG8_WAIT_L(0); PG8_BAR; PG8_MMA(0, 0, At, B0); PG8_MMA(0, 1, At, B1); PG8_BAR; PG8_SCHED;
;             PG8_LDA(At, 0, 1); PG8_STAGE(PG8_SB(0, 0), b2, voffB); PG8_STAGE(PG8_SB(0, 1), b2 + hstep, voffB); PG8_STAGE(PG8_SA(0, 0), a2, voffA);
;             PG8_WAIT_V(8); PG8_WAIT_L(0); PG8_BAR; PG8_MMA(1, 0, At, B0); PG8_MMA(1, 1, At, B1); PG8_BAR; PG8_SCHED;
;             PG8_LDB(B0, 1, 0); PG8_LDB(B1, 1, 1); PG8_SCHED; PG8_LDA(At, 1, 0); PG8_STAGE(PG8_SA(0, 1), a2 + hstep, voffA);
;             PG8_WAIT_V(8); PG8_WAIT_L(0); PG8_BAR; PG8_MMA(0, 0, At, B0); PG8_MMA(0, 1, At, B1); PG8_BAR; PG8_SCHED;
;             PG8_LDA(At, 1, 1); PG8_STAGE(PG8_SB(1, 0), b3, voffB); PG8_STAGE(PG8_SB(1, 1), b3 + hstep, voffB); PG8_STAGE(PG8_SA(1, 0), a3, voffA);
;             PG8_WAIT_V(8); PG8_WAIT_L(0); PG8_BAR; PG8_MMA(1, 0, At, B0); PG8_MMA(1, 1, At, B1); PG8_BAR; PG8_SCHED;
.LBB0_563:
	s_add_u32 s22, s20, 0x4000
	s_addc_u32 s23, s21, 0
	s_cmp_eq_u32 s78, 28
	s_cselect_b32 vcc_lo, s17, s22
	s_cselect_b32 vcc_hi, s9, s23
	s_cselect_b32 s86, s65, s67
	s_cselect_b32 s87, s7, s74
	s_add_u32 s52, vcc_lo, 0x2000
	s_addc_u32 s53, vcc_hi, 0
	s_add_i32 s79, 0, 0x10000
	v_add_u32_e32 v142, s79, v145
	s_add_i32 s83, 0, 0x14000
	ds_read_b128 v[150:153], v142
	ds_read_b128 v[154:157], v142 offset:1024
	ds_read_b128 v[158:161], v142 offset:2048
	ds_read_b128 v[162:165], v142 offset:3072
	v_add_u32_e32 v142, s83, v145
	ds_read_b128 v[166:169], v142
	ds_read_b128 v[184:187], v142 offset:1024
	ds_read_b128 v[188:191], v142 offset:2048
	ds_read_b128 v[192:195], v142 offset:3072
	v_lshl_add_u64 v[170:171], s[20:21], 0, v[138:139]
	s_add_i32 m0, s19, 0xc000
	ds_read_b128 v[196:199], v149
	ds_read_b128 v[200:203], v149 offset:1024
	ds_read_b128 v[204:207], v149 offset:2048
	ds_read_b128 v[208:211], v149 offset:3072
	ds_read_b128 v[228:231], v149 offset:4096
	ds_read_b128 v[232:235], v149 offset:5120
	ds_read_b128 v[236:239], v149 offset:6144
	ds_read_b128 v[240:243], v149 offset:7168
	global_load_lds_dwordx4 v[170:171], off
	v_lshl_add_u64 v[170:171], s[20:21], 0, v[140:141]
	s_add_i32 m0, s19, 0xe000
	s_nop 0
	global_load_lds_dwordx4 v[170:171], off
	s_waitcnt vmcnt(8)
	s_waitcnt lgkmcnt(0)
	s_barrier
	s_setprio 1
	s_waitcnt lgkmcnt(0)
	v_mfma_f32_16x16x32_bf16 v[128:131], v[150:153], v[196:199], v[128:131]
	v_mfma_f32_16x16x32_bf16 v[124:127], v[158:161], v[196:199], v[124:127]
	v_mfma_f32_16x16x32_bf16 v[112:115], v[150:153], v[204:207], v[112:115]
	v_mfma_f32_16x16x32_bf16 v[108:111], v[158:161], v[204:207], v[108:111]
	v_mfma_f32_16x16x32_bf16 v[96:99], v[150:153], v[228:231], v[96:99]
	v_mfma_f32_16x16x32_bf16 v[92:95], v[158:161], v[228:231], v[92:95]
	v_mfma_f32_16x16x32_bf16 v[80:83], v[150:153], v[236:239], v[80:83]
	v_mfma_f32_16x16x32_bf16 v[76:79], v[158:161], v[236:239], v[76:79]
	v_mfma_f32_16x16x32_bf16 v[128:131], v[154:157], v[200:203], v[128:131]
	v_mfma_f32_16x16x32_bf16 v[124:127], v[162:165], v[200:203], v[124:127]
	v_mfma_f32_16x16x32_bf16 v[112:115], v[154:157], v[208:211], v[112:115]
	v_mfma_f32_16x16x32_bf16 v[108:111], v[162:165], v[208:211], v[108:111]
	v_mfma_f32_16x16x32_bf16 v[96:99], v[154:157], v[232:235], v[96:99]
	v_mfma_f32_16x16x32_bf16 v[92:95], v[162:165], v[232:235], v[92:95]
	v_mfma_f32_16x16x32_bf16 v[80:83], v[154:157], v[240:243], v[80:83]
	v_mfma_f32_16x16x32_bf16 v[76:79], v[162:165], v[240:243], v[76:79]
	s_setprio 0
	s_setprio 1
	v_mfma_f32_16x16x32_bf16 v[120:123], v[166:169], v[196:199], v[120:123]
	v_mfma_f32_16x16x32_bf16 v[116:119], v[188:191], v[196:199], v[116:119]
	v_mfma_f32_16x16x32_bf16 v[104:107], v[166:169], v[204:207], v[104:107]
	v_mfma_f32_16x16x32_bf16 v[100:103], v[188:191], v[204:207], v[100:103]
	v_mfma_f32_16x16x32_bf16 v[88:91], v[166:169], v[228:231], v[88:91]
	v_mfma_f32_16x16x32_bf16 v[84:87], v[188:191], v[228:231], v[84:87]
	v_mfma_f32_16x16x32_bf16 v[72:75], v[166:169], v[236:239], v[72:75]
	v_mfma_f32_16x16x32_bf16 v[68:71], v[188:191], v[236:239], v[68:71]
	v_mfma_f32_16x16x32_bf16 v[120:123], v[184:187], v[200:203], v[120:123]
	v_mfma_f32_16x16x32_bf16 v[116:119], v[192:195], v[200:203], v[116:119]
	v_mfma_f32_16x16x32_bf16 v[104:107], v[184:187], v[208:211], v[104:107]
	v_mfma_f32_16x16x32_bf16 v[100:103], v[192:195], v[208:211], v[100:103]
	v_mfma_f32_16x16x32_bf16 v[88:91], v[184:187], v[232:235], v[88:91]
	v_mfma_f32_16x16x32_bf16 v[84:87], v[192:195], v[232:235], v[84:87]
	v_mfma_f32_16x16x32_bf16 v[72:75], v[184:187], v[240:243], v[72:75]
	v_mfma_f32_16x16x32_bf16 v[68:71], v[192:195], v[240:243], v[68:71]
	s_setprio 0
	s_barrier
	s_add_i32 s20, s79, s41
	v_lshl_add_u64 v[170:171], s[86:87], 0, v[2:3]
	s_mov_b32 m0, s20
	ds_read_b128 v[196:199], v149 offset:16384
	ds_read_b128 v[200:203], v149 offset:17408
	ds_read_b128 v[204:207], v149 offset:18432
	ds_read_b128 v[208:211], v149 offset:19456
	ds_read_b128 v[228:231], v149 offset:20480
	ds_read_b128 v[232:235], v149 offset:21504
	ds_read_b128 v[236:239], v149 offset:22528
	ds_read_b128 v[240:243], v149 offset:23552
	global_load_lds_dwordx4 v[170:171], off
	s_add_i32 m0, s20, 0x2000
	s_add_u32 s20, s86, 0x80000
	v_lshl_add_u64 v[170:171], s[86:87], 0, v[132:133]
	s_addc_u32 s21, s87, 0
	s_add_i32 s79, s83, s41
	global_load_lds_dwordx4 v[170:171], off
	v_lshl_add_u64 v[170:171], s[20:21], 0, v[2:3]
	s_mov_b32 m0, s79
	s_nop 0
	global_load_lds_dwordx4 v[170:171], off
	v_lshl_add_u64 v[170:171], s[20:21], 0, v[132:133]
	s_add_i32 m0, s79, 0x2000
	s_nop 0
	global_load_lds_dwordx4 v[170:171], off
	v_lshl_add_u64 v[170:171], vcc, 0, v[136:137]
	s_mov_b32 m0, s19
	s_nop 0
	global_load_lds_dwordx4 v[170:171], off
	v_lshl_add_u64 v[170:171], vcc, 0, v[134:135]
	s_mov_b32 m0, s45
	s_nop 0
	global_load_lds_dwordx4 v[170:171], off
	s_waitcnt vmcnt(8)
	s_waitcnt lgkmcnt(0)
	s_barrier
; #define PG8_WAIT_V(n) asm volatile("s_waitcnt vmcnt(" #n ")" ::: "memory")
; #define PG8_WAIT_L(n) asm volatile("s_waitcnt lgkmcnt(" #n ")" ::: "memory")
; #define PG8_BAR __builtin_amdgcn_s_barrier()
; #define PG8_SCHED __builtin_amdgcn_sched_barrier(0)
; template <class Epi, class Sched, bool ALIGN_EPI = false, bool SP2 = false, bool F8 = false>
; __device__ __forceinline__ void gemm_phase(PG8_LAS unsigned char* lds, const Gemm g, const Sched& S, const Epi& E) {
;     ...
;             PG8_LDB(B0, 0, 0); PG8_LDB(B1, 0, 1); PG8_SCHED; PG8_LDA(At, 0, 0); PG8_STAGE(PG8_SA(1, 1), a1 + hstep, voffA);
;             PG8_WAIT_V(8); PG8_WAIT_L(0); PG8_BAR; PG8_MMA(0, 0, At, B0); PG8_MMA(0, 1, At, B1); PG8_BAR; PG8_SCHED;
;             PG8_LDA(At, 0, 1); PG8_STAGE(PG8_SB(0, 0), b2, voffB); PG8_STAGE(PG8_SB(0, 1), b2 + hstep, voffB); PG8_STAGE(PG8_SA(0, 0), a2, voffA);
;             PG8_WAIT_V(8); PG8_WAIT_L(0); PG8_BAR; PG8_MMA(1, 0, At, B0); PG8_MMA(1, 1, At, B1); PG8_BAR; PG8_SCHED;
;             PG8_LDB(B0, 1, 0); PG8_LDB(B1, 1, 1); PG8_SCHED; PG8_LDA(At, 1, 0); PG8_STAGE(PG8_SA(0, 1), a2 + hstep, voffA);
;             PG8_WAIT_V(8); PG8_WAIT_L(0); PG8_BAR; PG8_MMA(0, 0, At, B0); PG8_MMA(0, 1, At, B1); PG8_BAR; PG8_SCHED;
;             PG8_LDA(At, 1, 1); PG8_STAGE(PG8_SB(1, 0), b3, voffB); PG8_STAGE(PG8_SB(1, 1), b3 + hstep, voffB); PG8_STAGE(PG8_SA(1, 0), a3, voffA);
;             PG8_WAIT_V(8); PG8_WAIT_L(0); PG8_BAR; PG8_MMA(1, 0, At, B0); PG8_MMA(1, 1, At, B1); PG8_BAR; PG8_SCHED;
	s_setprio 1
	s_waitcnt lgkmcnt(0)
	v_mfma_f32_16x16x32_bf16 v[64:67], v[150:153], v[196:199], v[64:67]
	v_mfma_f32_16x16x32_bf16 v[60:63], v[158:161], v[196:199], v[60:63]
	v_mfma_f32_16x16x32_bf16 v[48:51], v[150:153], v[204:207], v[48:51]
	v_mfma_f32_16x16x32_bf16 v[44:47], v[158:161], v[204:207], v[44:47]
	v_mfma_f32_16x16x32_bf16 v[32:35], v[150:153], v[228:231], v[32:35]
	v_mfma_f32_16x16x32_bf16 v[28:31], v[158:161], v[228:231], v[28:31]
	v_mfma_f32_16x16x32_bf16 v[16:19], v[150:153], v[236:239], v[16:19]
	v_mfma_f32_16x16x32_bf16 v[12:15], v[158:161], v[236:239], v[12:15]
	v_mfma_f32_16x16x32_bf16 v[64:67], v[154:157], v[200:203], v[64:67]
	v_mfma_f32_16x16x32_bf16 v[60:63], v[162:165], v[200:203], v[60:63]
	v_mfma_f32_16x16x32_bf16 v[48:51], v[154:157], v[208:211], v[48:51]
	v_mfma_f32_16x16x32_bf16 v[44:47], v[162:165], v[208:211], v[44:47]
	v_mfma_f32_16x16x32_bf16 v[32:35], v[154:157], v[232:235], v[32:35]
	v_mfma_f32_16x16x32_bf16 v[28:31], v[162:165], v[232:235], v[28:31]
	v_mfma_f32_16x16x32_bf16 v[16:19], v[154:157], v[240:243], v[16:19]
	v_mfma_f32_16x16x32_bf16 v[12:15], v[162:165], v[240:243], v[12:15]
	s_setprio 0
	s_setprio 1
	v_mfma_f32_16x16x32_bf16 v[56:59], v[166:169], v[196:199], v[56:59]
	v_mfma_f32_16x16x32_bf16 v[52:55], v[188:191], v[196:199], v[52:55]
	v_mfma_f32_16x16x32_bf16 v[40:43], v[166:169], v[204:207], v[40:43]
	v_mfma_f32_16x16x32_bf16 v[36:39], v[188:191], v[204:207], v[36:39]
	v_mfma_f32_16x16x32_bf16 v[24:27], v[166:169], v[228:231], v[24:27]
	v_mfma_f32_16x16x32_bf16 v[20:23], v[188:191], v[228:231], v[20:23]
	v_mfma_f32_16x16x32_bf16 v[8:11], v[166:169], v[236:239], v[8:11]
	v_mfma_f32_16x16x32_bf16 v[4:7], v[188:191], v[236:239], v[4:7]
	v_mfma_f32_16x16x32_bf16 v[56:59], v[184:187], v[200:203], v[56:59]
	v_mfma_f32_16x16x32_bf16 v[52:55], v[192:195], v[200:203], v[52:55]
	v_mfma_f32_16x16x32_bf16 v[40:43], v[184:187], v[208:211], v[40:43]
	v_mfma_f32_16x16x32_bf16 v[36:39], v[192:195], v[208:211], v[36:39]
	v_mfma_f32_16x16x32_bf16 v[24:27], v[184:187], v[232:235], v[24:27]
	v_mfma_f32_16x16x32_bf16 v[20:23], v[192:195], v[232:235], v[20:23]
	v_mfma_f32_16x16x32_bf16 v[8:11], v[184:187], v[240:243], v[8:11]
	v_mfma_f32_16x16x32_bf16 v[4:7], v[192:195], v[240:243], v[4:7]
	s_setprio 0
	s_barrier
	s_add_i32 s79, 0, 0x18000
	v_add_u32_e32 v142, s79, v145
	s_add_i32 s83, 0, 0x1c000
	ds_read_b128 v[150:153], v142
	ds_read_b128 v[154:157], v142 offset:1024
	ds_read_b128 v[158:161], v142 offset:2048
	ds_read_b128 v[162:165], v142 offset:3072
	v_add_u32_e32 v142, s83, v145
	ds_read_b128 v[166:169], v142
	ds_read_b128 v[184:187], v142 offset:1024
	ds_read_b128 v[188:191], v142 offset:2048
	ds_read_b128 v[192:195], v142 offset:3072
	s_add_u32 s20, vcc_lo, 0x80000
	s_addc_u32 s21, vcc_hi, 0
	s_mov_b32 m0, s48
	v_lshl_add_u64 v[170:171], s[20:21], 0, v[136:137]
	ds_read_b128 v[196:199], v149 offset:32768
	ds_read_b128 v[200:203], v149 offset:33792
	ds_read_b128 v[204:207], v149 offset:34816
	ds_read_b128 v[208:211], v149 offset:35840
	ds_read_b128 v[228:231], v149 offset:36864
	ds_read_b128 v[232:235], v149 offset:37888
	ds_read_b128 v[236:239], v149 offset:38912
	ds_read_b128 v[240:243], v149 offset:39936
	global_load_lds_dwordx4 v[170:171], off
	v_lshl_add_u64 v[170:171], s[20:21], 0, v[134:135]
	s_mov_b32 m0, s49
	s_nop 0
	global_load_lds_dwordx4 v[170:171], off
	s_waitcnt vmcnt(8)
	s_waitcnt lgkmcnt(0)
	s_nop 0
	s_barrier
	s_setprio 1
	s_waitcnt lgkmcnt(0)
	v_mfma_f32_16x16x32_bf16 v[128:131], v[150:153], v[196:199], v[128:131]
	v_mfma_f32_16x16x32_bf16 v[124:127], v[158:161], v[196:199], v[124:127]
	v_mfma_f32_16x16x32_bf16 v[112:115], v[150:153], v[204:207], v[112:115]
	v_mfma_f32_16x16x32_bf16 v[108:111], v[158:161], v[204:207], v[108:111]
	v_mfma_f32_16x16x32_bf16 v[96:99], v[150:153], v[228:231], v[96:99]
	v_mfma_f32_16x16x32_bf16 v[92:95], v[158:161], v[228:231], v[92:95]
	v_mfma_f32_16x16x32_bf16 v[80:83], v[150:153], v[236:239], v[80:83]
	v_mfma_f32_16x16x32_bf16 v[76:79], v[158:161], v[236:239], v[76:79]
	v_mfma_f32_16x16x32_bf16 v[128:131], v[154:157], v[200:203], v[128:131]
	v_mfma_f32_16x16x32_bf16 v[124:127], v[162:165], v[200:203], v[124:127]
	v_mfma_f32_16x16x32_bf16 v[112:115], v[154:157], v[208:211], v[112:115]
	v_mfma_f32_16x16x32_bf16 v[108:111], v[162:165], v[208:211], v[108:111]
	v_mfma_f32_16x16x32_bf16 v[96:99], v[154:157], v[232:235], v[96:99]
	v_mfma_f32_16x16x32_bf16 v[92:95], v[162:165], v[232:235], v[92:95]
	v_mfma_f32_16x16x32_bf16 v[80:83], v[154:157], v[240:243], v[80:83]
	v_mfma_f32_16x16x32_bf16 v[76:79], v[162:165], v[240:243], v[76:79]
	s_setprio 0
	s_setprio 1
	v_mfma_f32_16x16x32_bf16 v[120:123], v[166:169], v[196:199], v[120:123]
	v_mfma_f32_16x16x32_bf16 v[116:119], v[188:191], v[196:199], v[116:119]
	v_mfma_f32_16x16x32_bf16 v[104:107], v[166:169], v[204:207], v[104:107]
	v_mfma_f32_16x16x32_bf16 v[100:103], v[188:191], v[204:207], v[100:103]
	v_mfma_f32_16x16x32_bf16 v[88:91], v[166:169], v[228:231], v[88:91]
	v_mfma_f32_16x16x32_bf16 v[84:87], v[188:191], v[228:231], v[84:87]
	v_mfma_f32_16x16x32_bf16 v[72:75], v[166:169], v[236:239], v[72:75]
	v_mfma_f32_16x16x32_bf16 v[68:71], v[188:191], v[236:239], v[68:71]
	v_mfma_f32_16x16x32_bf16 v[120:123], v[184:187], v[200:203], v[120:123]
	v_mfma_f32_16x16x32_bf16 v[116:119], v[192:195], v[200:203], v[116:119]
	v_mfma_f32_16x16x32_bf16 v[104:107], v[184:187], v[208:211], v[104:107]
	v_mfma_f32_16x16x32_bf16 v[100:103], v[192:195], v[208:211], v[100:103]
	v_mfma_f32_16x16x32_bf16 v[88:91], v[184:187], v[232:235], v[88:91]
	v_mfma_f32_16x16x32_bf16 v[84:87], v[192:195], v[232:235], v[84:87]
	v_mfma_f32_16x16x32_bf16 v[72:75], v[184:187], v[240:243], v[72:75]
	v_mfma_f32_16x16x32_bf16 v[68:71], v[192:195], v[240:243], v[68:71]
	s_setprio 0
	s_barrier
; #define PG8_WAIT_V(n) asm volatile("s_waitcnt vmcnt(" #n ")" ::: "memory")
; #define PG8_WAIT_L(n) asm volatile("s_waitcnt lgkmcnt(" #n ")" ::: "memory")
; #define PG8_BAR __builtin_amdgcn_s_barrier()
; #define PG8_SCHED __builtin_amdgcn_sched_barrier(0)
; template <class Epi, class Sched, bool ALIGN_EPI = false, bool SP2 = false, bool F8 = false>
; __device__ __forceinline__ void gemm_phase(PG8_LAS unsigned char* lds, const Gemm g, const Sched& S, const Epi& E) {
;     ...
;             PG8_LDB(B0, 0, 0); PG8_LDB(B1, 0, 1); PG8_SCHED; PG8_LDA(At, 0, 0); PG8_STAGE(PG8_SA(1, 1), a1 + hstep, voffA);
;             PG8_WAIT_V(8); PG8_WAIT_L(0); PG8_BAR; PG8_MMA(0, 0, At, B0); PG8_MMA(0, 1, At, B1); PG8_BAR; PG8_SCHED;
;             PG8_LDA(At, 0, 1); PG8_STAGE(PG8_SB(0, 0), b2, voffB); PG8_STAGE(PG8_SB(0, 1), b2 + hstep, voffB); PG8_STAGE(PG8_SA(0, 0), a2, voffA);
;             PG8_WAIT_V(8); PG8_WAIT_L(0); PG8_BAR; PG8_MMA(1, 0, At, B0); PG8_MMA(1, 1, At, B1); PG8_BAR; PG8_SCHED;
;             PG8_LDB(B0, 1, 0); PG8_LDB(B1, 1, 1); PG8_SCHED; PG8_LDA(At, 1, 0); PG8_STAGE(PG8_SA(0, 1), a2 + hstep, voffA);
;             PG8_WAIT_V(8); PG8_WAIT_L(0); PG8_BAR; PG8_MMA(0, 0, At, B0); PG8_MMA(0, 1, At, B1); PG8_BAR; PG8_SCHED;
;             PG8_LDA(At, 1, 1); PG8_STAGE(PG8_SB(1, 0), b3, voffB); PG8_STAGE(PG8_SB(1, 1), b3 + hstep, voffB); PG8_STAGE(PG8_SA(1, 0), a3, voffA);
;             PG8_WAIT_V(8); PG8_WAIT_L(0); PG8_BAR; PG8_MMA(1, 0, At, B0); PG8_MMA(1, 1, At, B1); PG8_BAR; PG8_SCHED;
	s_add_u32 s20, s86, 0x2000
	s_addc_u32 s21, s87, 0
	s_add_i32 s79, s79, s41
	v_lshl_add_u64 v[170:171], s[20:21], 0, v[2:3]
	s_mov_b32 m0, s79
	ds_read_b128 v[196:199], v149 offset:49152
	ds_read_b128 v[200:203], v149 offset:50176
	ds_read_b128 v[204:207], v149 offset:51200
	ds_read_b128 v[208:211], v149 offset:52224
	ds_read_b128 v[228:231], v149 offset:53248
	ds_read_b128 v[232:235], v149 offset:54272
	ds_read_b128 v[236:239], v149 offset:55296
	ds_read_b128 v[240:243], v149 offset:56320
	global_load_lds_dwordx4 v[170:171], off
	s_add_i32 m0, s79, 0x2000
	v_lshl_add_u64 v[170:171], s[20:21], 0, v[132:133]
	s_add_u32 s20, s86, 0x82000
	s_addc_u32 s21, s87, 0
	s_add_i32 s79, s83, s41
	global_load_lds_dwordx4 v[170:171], off
	v_lshl_add_u64 v[170:171], s[20:21], 0, v[2:3]
	s_mov_b32 m0, s79
	s_nop 0
	global_load_lds_dwordx4 v[170:171], off
	v_lshl_add_u64 v[170:171], s[20:21], 0, v[132:133]
	s_add_i32 m0, s79, 0x2000
	s_nop 0
	global_load_lds_dwordx4 v[170:171], off
	v_lshl_add_u64 v[170:171], s[52:53], 0, v[136:137]
	s_mov_b32 m0, s50
	s_nop 0
	global_load_lds_dwordx4 v[170:171], off
	v_lshl_add_u64 v[170:171], s[52:53], 0, v[134:135]
	s_mov_b32 m0, s55
	s_nop 0
	global_load_lds_dwordx4 v[170:171], off
	s_waitcnt vmcnt(8)
	s_waitcnt lgkmcnt(0)
	s_nop 0
	s_barrier
	s_setprio 1
	s_waitcnt lgkmcnt(0)
	v_mfma_f32_16x16x32_bf16 v[64:67], v[150:153], v[196:199], v[64:67]
	v_mfma_f32_16x16x32_bf16 v[60:63], v[158:161], v[196:199], v[60:63]
	v_mfma_f32_16x16x32_bf16 v[48:51], v[150:153], v[204:207], v[48:51]
	v_mfma_f32_16x16x32_bf16 v[44:47], v[158:161], v[204:207], v[44:47]
	v_mfma_f32_16x16x32_bf16 v[32:35], v[150:153], v[228:231], v[32:35]
	v_mfma_f32_16x16x32_bf16 v[28:31], v[158:161], v[228:231], v[28:31]
	v_mfma_f32_16x16x32_bf16 v[16:19], v[150:153], v[236:239], v[16:19]
	v_mfma_f32_16x16x32_bf16 v[12:15], v[158:161], v[236:239], v[12:15]
	v_mfma_f32_16x16x32_bf16 v[64:67], v[154:157], v[200:203], v[64:67]
	v_mfma_f32_16x16x32_bf16 v[60:63], v[162:165], v[200:203], v[60:63]
	v_mfma_f32_16x16x32_bf16 v[48:51], v[154:157], v[208:211], v[48:51]
	v_mfma_f32_16x16x32_bf16 v[44:47], v[162:165], v[208:211], v[44:47]
	v_mfma_f32_16x16x32_bf16 v[32:35], v[154:157], v[232:235], v[32:35]
	v_mfma_f32_16x16x32_bf16 v[28:31], v[162:165], v[232:235], v[28:31]
	v_mfma_f32_16x16x32_bf16 v[16:19], v[154:157], v[240:243], v[16:19]
	v_mfma_f32_16x16x32_bf16 v[12:15], v[162:165], v[240:243], v[12:15]
	s_setprio 0
	s_setprio 1
	v_mfma_f32_16x16x32_bf16 v[56:59], v[166:169], v[196:199], v[56:59]
	v_mfma_f32_16x16x32_bf16 v[52:55], v[188:191], v[196:199], v[52:55]
	v_mfma_f32_16x16x32_bf16 v[40:43], v[166:169], v[204:207], v[40:43]
	v_mfma_f32_16x16x32_bf16 v[36:39], v[188:191], v[204:207], v[36:39]
	v_mfma_f32_16x16x32_bf16 v[24:27], v[166:169], v[228:231], v[24:27]
	v_mfma_f32_16x16x32_bf16 v[20:23], v[188:191], v[228:231], v[20:23]
	v_mfma_f32_16x16x32_bf16 v[8:11], v[166:169], v[236:239], v[8:11]
	v_mfma_f32_16x16x32_bf16 v[4:7], v[188:191], v[236:239], v[4:7]
	v_mfma_f32_16x16x32_bf16 v[56:59], v[184:187], v[200:203], v[56:59]
	v_mfma_f32_16x16x32_bf16 v[52:55], v[192:195], v[200:203], v[52:55]
	v_mfma_f32_16x16x32_bf16 v[40:43], v[184:187], v[208:211], v[40:43]
	v_mfma_f32_16x16x32_bf16 v[36:39], v[192:195], v[208:211], v[36:39]
	v_mfma_f32_16x16x32_bf16 v[24:27], v[184:187], v[232:235], v[24:27]
	v_mfma_f32_16x16x32_bf16 v[20:23], v[192:195], v[232:235], v[20:23]
	v_mfma_f32_16x16x32_bf16 v[8:11], v[184:187], v[240:243], v[8:11]
	v_mfma_f32_16x16x32_bf16 v[4:7], v[192:195], v[240:243], v[4:7]
	s_setprio 0
	s_barrier
	s_add_i32 s78, s78, 2
	s_add_u32 s67, s67, 0x4000
	s_addc_u32 s74, s74, 0
	s_cmp_gt_u32 s78, 29
	s_mov_b64 s[20:21], s[22:23]
	s_cbranch_scc0 .LBB0_563
	s_and_b64 vcc, exec, s[4:5]
	s_cbranch_vccz .LBB0_566
	s_barrier

; #define PG8_WAIT_V(n) asm volatile("s_waitcnt vmcnt(" #n ")" ::: "memory")
; #define PG8_WAIT_L(n) asm volatile("s_waitcnt lgkmcnt(" #n ")" ::: "memory")
; #define PG8_BAR __builtin_amdgcn_s_barrier()
; #define PG8_SCHED __builtin_amdgcn_sched_barrier(0)
; template <class Epi, class Sched, bool ALIGN_EPI = false, bool SP2 = false, bool F8 = false>
; __device__ __forceinline__ void gemm_phase(PG8_LAS unsigned char* lds, const Gemm g, const Sched& S, const Epi& E) {
;     ...
;             PG8_LDB(B0, 0, 0); PG8_LDB(B1, 0, 1); PG8_SCHED; PG8_LDA(At, 0, 0); PG8_STAGE(PG8_SA(1, 1), a1 + hstep, voffA);
;             PG8_WAIT_V(8); PG8_WAIT_L(0); PG8_BAR; PG8_MMA(0, 0, At, B0); PG8_MMA(0, 1, At, B1); PG8_BAR; PG8_SCHED;
;             PG8_LDA(At, 0, 1); PG8_STAGE(PG8_SB(0, 0), b2, voffB); PG8_STAGE(PG8_SB(0, 1), b2 + hstep, voffB); PG8_STAGE(PG8_SA(0, 0), a2, voffA);
;             PG8_WAIT_V(8); PG8_WAIT_L(0); PG8_BAR; PG8_MMA(1, 0, At, B0); PG8_MMA(1, 1, At, B1); PG8_BAR; PG8_SCHED;
;             PG8_LDB(B0, 1, 0); PG8_LDB(B1, 1, 1); PG8_SCHED; PG8_LDA(At, 1, 0); PG8_STAGE(PG8_SA(0, 1), a2 + hstep, voffA);
;             PG8_WAIT_V(8); PG8_WAIT_L(0); PG8_BAR; PG8_MMA(0, 0, At, B0); PG8_MMA(0, 1, At, B1); PG8_BAR; PG8_SCHED;
;             PG8_LDA(At, 1, 1); PG8_STAGE(PG8_SB(1, 0), b3, voffB); PG8_STAGE(PG8_SB(1, 1), b3 + hstep, voffB); PG8_STAGE(PG8_SA(1, 0), a3, voffA);
;             PG8_WAIT_V(8); PG8_WAIT_L(0); PG8_BAR; PG8_MMA(1, 0, At, B0); PG8_MMA(1, 1, At, B1); PG8_BAR; PG8_SCHED;
.LBB0_1314:
	s_add_u32 s14, s6, 0x4000
	s_addc_u32 s15, s7, 0
	s_cmp_eq_u32 s48, 8
	s_cselect_b32 s20, s0, s14
	s_cselect_b32 s21, s1, s15
	s_cselect_b32 s18, s12, s40
	s_cselect_b32 s19, s13, s41
	s_add_u32 s16, s20, 0x2000
	s_addc_u32 s17, s21, 0
	s_add_i32 s49, 0, 0x10000
	v_add_u32_e32 v2, s49, v145
	s_add_i32 s50, 0, 0x14000
	ds_read_b128 v[150:153], v2
	s_waitcnt vmcnt(0)
	ds_read_b128 v[154:157], v2 offset:1024
	ds_read_b128 v[158:161], v2 offset:2048
	ds_read_b128 v[162:165], v2 offset:3072
	v_add_u32_e32 v2, s50, v145
	ds_read_b128 v[166:169], v2
	ds_read_b128 v[170:173], v2 offset:1024
	ds_read_b128 v[174:177], v2 offset:2048
	ds_read_b128 v[178:181], v2 offset:3072
	v_lshl_add_u64 v[214:215], s[6:7], 0, v[146:147]
	s_add_i32 m0, s25, 0xc000
	ds_read_b128 v[182:185], v228
	ds_read_b128 v[186:189], v228 offset:1024
	ds_read_b128 v[190:193], v228 offset:2048
	ds_read_b128 v[194:197], v228 offset:3072
	ds_read_b128 v[198:201], v228 offset:4096
	ds_read_b128 v[202:205], v228 offset:5120
	ds_read_b128 v[206:209], v228 offset:6144
	ds_read_b128 v[210:213], v228 offset:7168
	global_load_lds_dwordx4 v[214:215], off
	v_lshl_add_u64 v[214:215], s[6:7], 0, v[148:149]
	s_add_i32 m0, s25, 0xe000
	s_nop 0
	global_load_lds_dwordx4 v[214:215], off
	s_waitcnt vmcnt(8)
	s_waitcnt lgkmcnt(0)
	s_barrier
	s_setprio 1
	s_waitcnt lgkmcnt(0)
	v_mfma_f32_16x16x32_bf16 v[128:131], v[150:153], v[182:185], v[128:131]
	v_mfma_f32_16x16x32_bf16 v[124:127], v[158:161], v[182:185], v[124:127]
	v_mfma_f32_16x16x32_bf16 v[120:123], v[150:153], v[190:193], v[120:123]
	v_mfma_f32_16x16x32_bf16 v[116:119], v[158:161], v[190:193], v[116:119]
	v_mfma_f32_16x16x32_bf16 v[112:115], v[150:153], v[198:201], v[112:115]
	v_mfma_f32_16x16x32_bf16 v[108:111], v[158:161], v[198:201], v[108:111]
	v_mfma_f32_16x16x32_bf16 v[104:107], v[150:153], v[206:209], v[104:107]
	v_mfma_f32_16x16x32_bf16 v[100:103], v[158:161], v[206:209], v[100:103]
	v_mfma_f32_16x16x32_bf16 v[128:131], v[154:157], v[186:189], v[128:131]
	v_mfma_f32_16x16x32_bf16 v[124:127], v[162:165], v[186:189], v[124:127]
	v_mfma_f32_16x16x32_bf16 v[120:123], v[154:157], v[194:197], v[120:123]
	v_mfma_f32_16x16x32_bf16 v[116:119], v[162:165], v[194:197], v[116:119]
	v_mfma_f32_16x16x32_bf16 v[112:115], v[154:157], v[202:205], v[112:115]
	v_mfma_f32_16x16x32_bf16 v[108:111], v[162:165], v[202:205], v[108:111]
	v_mfma_f32_16x16x32_bf16 v[104:107], v[154:157], v[210:213], v[104:107]
	v_mfma_f32_16x16x32_bf16 v[100:103], v[162:165], v[210:213], v[100:103]
	s_setprio 0
	s_setprio 1
	v_mfma_f32_16x16x32_bf16 v[96:99], v[166:169], v[182:185], v[96:99]
	v_mfma_f32_16x16x32_bf16 v[92:95], v[174:177], v[182:185], v[92:95]
	v_mfma_f32_16x16x32_bf16 v[88:91], v[166:169], v[190:193], v[88:91]
	v_mfma_f32_16x16x32_bf16 v[84:87], v[174:177], v[190:193], v[84:87]
	v_mfma_f32_16x16x32_bf16 v[80:83], v[166:169], v[198:201], v[80:83]
	v_mfma_f32_16x16x32_bf16 v[76:79], v[174:177], v[198:201], v[76:79]
	v_mfma_f32_16x16x32_bf16 v[72:75], v[166:169], v[206:209], v[72:75]
	v_mfma_f32_16x16x32_bf16 v[68:71], v[174:177], v[206:209], v[68:71]
	v_mfma_f32_16x16x32_bf16 v[96:99], v[170:173], v[186:189], v[96:99]
	v_mfma_f32_16x16x32_bf16 v[92:95], v[178:181], v[186:189], v[92:95]
	v_mfma_f32_16x16x32_bf16 v[88:91], v[170:173], v[194:197], v[88:91]
	v_mfma_f32_16x16x32_bf16 v[84:87], v[178:181], v[194:197], v[84:87]
	v_mfma_f32_16x16x32_bf16 v[80:83], v[170:173], v[202:205], v[80:83]
	v_mfma_f32_16x16x32_bf16 v[76:79], v[178:181], v[202:205], v[76:79]
	v_mfma_f32_16x16x32_bf16 v[72:75], v[170:173], v[210:213], v[72:75]
	v_mfma_f32_16x16x32_bf16 v[68:71], v[178:181], v[210:213], v[68:71]
	s_setprio 0
	s_barrier
	s_add_i32 s6, s49, s24
	v_lshl_add_u64 v[214:215], s[18:19], 0, v[136:137]
	s_mov_b32 m0, s6
	ds_read_b128 v[182:185], v228 offset:16384
	ds_read_b128 v[186:189], v228 offset:17408
	ds_read_b128 v[190:193], v228 offset:18432
	ds_read_b128 v[194:197], v228 offset:19456
	ds_read_b128 v[198:201], v228 offset:20480
	ds_read_b128 v[202:205], v228 offset:21504
	ds_read_b128 v[206:209], v228 offset:22528
	ds_read_b128 v[210:213], v228 offset:23552
	global_load_lds_dwordx4 v[214:215], off
	s_add_i32 m0, s6, 0x2000
	s_add_u32 s6, s18, 0x30000
	v_lshl_add_u64 v[214:215], s[18:19], 0, v[132:133]
	s_addc_u32 s7, s19, 0
	s_add_i32 s49, s50, s24
	global_load_lds_dwordx4 v[214:215], off
	v_lshl_add_u64 v[214:215], s[6:7], 0, v[136:137]
	s_mov_b32 m0, s49
	s_nop 0
	global_load_lds_dwordx4 v[214:215], off
	v_lshl_add_u64 v[214:215], s[6:7], 0, v[132:133]
	s_add_i32 m0, s49, 0x2000
	s_nop 0
	global_load_lds_dwordx4 v[214:215], off
	v_lshl_add_u64 v[214:215], s[20:21], 0, v[138:139]
	s_mov_b32 m0, s25
	s_nop 0
	global_load_lds_dwordx4 v[214:215], off
	v_lshl_add_u64 v[214:215], s[20:21], 0, v[134:135]
	s_mov_b32 m0, s28
	s_nop 0
	global_load_lds_dwordx4 v[214:215], off
	s_waitcnt vmcnt(8)
	s_waitcnt lgkmcnt(0)
	s_barrier
; #define PG8_WAIT_V(n) asm volatile("s_waitcnt vmcnt(" #n ")" ::: "memory")
; #define PG8_WAIT_L(n) asm volatile("s_waitcnt lgkmcnt(" #n ")" ::: "memory")
; #define PG8_BAR __builtin_amdgcn_s_barrier()
; #define PG8_SCHED __builtin_amdgcn_sched_barrier(0)
; template <class Epi, class Sched, bool ALIGN_EPI = false, bool SP2 = false, bool F8 = false>
; __device__ __forceinline__ void gemm_phase(PG8_LAS unsigned char* lds, const Gemm g, const Sched& S, const Epi& E) {
;     ...
;             PG8_LDB(B0, 0, 0); PG8_LDB(B1, 0, 1); PG8_SCHED; PG8_LDA(At, 0, 0); PG8_STAGE(PG8_SA(1, 1), a1 + hstep, voffA);
;             PG8_WAIT_V(8); PG8_WAIT_L(0); PG8_BAR; PG8_MMA(0, 0, At, B0); PG8_MMA(0, 1, At, B1); PG8_BAR; PG8_SCHED;
;             PG8_LDA(At, 0, 1); PG8_STAGE(PG8_SB(0, 0), b2, voffB); PG8_STAGE(PG8_SB(0, 1), b2 + hstep, voffB); PG8_STAGE(PG8_SA(0, 0), a2, voffA);
;             PG8_WAIT_V(8); PG8_WAIT_L(0); PG8_BAR; PG8_MMA(1, 0, At, B0); PG8_MMA(1, 1, At, B1); PG8_BAR; PG8_SCHED;
;             PG8_LDB(B0, 1, 0); PG8_LDB(B1, 1, 1); PG8_SCHED; PG8_LDA(At, 1, 0); PG8_STAGE(PG8_SA(0, 1), a2 + hstep, voffA);
;             PG8_WAIT_V(8); PG8_WAIT_L(0); PG8_BAR; PG8_MMA(0, 0, At, B0); PG8_MMA(0, 1, At, B1); PG8_BAR; PG8_SCHED;
;             PG8_LDA(At, 1, 1); PG8_STAGE(PG8_SB(1, 0), b3, voffB); PG8_STAGE(PG8_SB(1, 1), b3 + hstep, voffB); PG8_STAGE(PG8_SA(1, 0), a3, voffA);
;             PG8_WAIT_V(8); PG8_WAIT_L(0); PG8_BAR; PG8_MMA(1, 0, At, B0); PG8_MMA(1, 1, At, B1); PG8_BAR; PG8_SCHED;
	s_setprio 1
	s_waitcnt lgkmcnt(0)
	v_mfma_f32_16x16x32_bf16 v[64:67], v[150:153], v[182:185], v[64:67]
	v_mfma_f32_16x16x32_bf16 v[60:63], v[158:161], v[182:185], v[60:63]
	v_mfma_f32_16x16x32_bf16 v[56:59], v[150:153], v[190:193], v[56:59]
	v_mfma_f32_16x16x32_bf16 v[52:55], v[158:161], v[190:193], v[52:55]
	v_mfma_f32_16x16x32_bf16 v[48:51], v[150:153], v[198:201], v[48:51]
	v_mfma_f32_16x16x32_bf16 v[44:47], v[158:161], v[198:201], v[44:47]
	v_mfma_f32_16x16x32_bf16 v[40:43], v[150:153], v[206:209], v[40:43]
	v_mfma_f32_16x16x32_bf16 v[36:39], v[158:161], v[206:209], v[36:39]
	v_mfma_f32_16x16x32_bf16 v[64:67], v[154:157], v[186:189], v[64:67]
	v_mfma_f32_16x16x32_bf16 v[60:63], v[162:165], v[186:189], v[60:63]
	v_mfma_f32_16x16x32_bf16 v[56:59], v[154:157], v[194:197], v[56:59]
	v_mfma_f32_16x16x32_bf16 v[52:55], v[162:165], v[194:197], v[52:55]
	v_mfma_f32_16x16x32_bf16 v[48:51], v[154:157], v[202:205], v[48:51]
	v_mfma_f32_16x16x32_bf16 v[44:47], v[162:165], v[202:205], v[44:47]
	v_mfma_f32_16x16x32_bf16 v[40:43], v[154:157], v[210:213], v[40:43]
	v_mfma_f32_16x16x32_bf16 v[36:39], v[162:165], v[210:213], v[36:39]
	s_setprio 0
	s_setprio 1
	v_mfma_f32_16x16x32_bf16 v[32:35], v[166:169], v[182:185], v[32:35]
	v_mfma_f32_16x16x32_bf16 v[28:31], v[174:177], v[182:185], v[28:31]
	v_mfma_f32_16x16x32_bf16 v[24:27], v[166:169], v[190:193], v[24:27]
	v_mfma_f32_16x16x32_bf16 v[20:23], v[174:177], v[190:193], v[20:23]
	v_mfma_f32_16x16x32_bf16 v[16:19], v[166:169], v[198:201], v[16:19]
	v_mfma_f32_16x16x32_bf16 v[12:15], v[174:177], v[198:201], v[12:15]
	v_mfma_f32_16x16x32_bf16 v[8:11], v[166:169], v[206:209], v[8:11]
	v_mfma_f32_16x16x32_bf16 v[4:7], v[174:177], v[206:209], v[4:7]
	v_mfma_f32_16x16x32_bf16 v[32:35], v[170:173], v[186:189], v[32:35]
	v_mfma_f32_16x16x32_bf16 v[28:31], v[178:181], v[186:189], v[28:31]
	v_mfma_f32_16x16x32_bf16 v[24:27], v[170:173], v[194:197], v[24:27]
	v_mfma_f32_16x16x32_bf16 v[20:23], v[178:181], v[194:197], v[20:23]
	v_mfma_f32_16x16x32_bf16 v[16:19], v[170:173], v[202:205], v[16:19]
	v_mfma_f32_16x16x32_bf16 v[12:15], v[178:181], v[202:205], v[12:15]
	v_mfma_f32_16x16x32_bf16 v[8:11], v[170:173], v[210:213], v[8:11]
	v_mfma_f32_16x16x32_bf16 v[4:7], v[178:181], v[210:213], v[4:7]
	s_setprio 0
	s_barrier
	s_add_i32 s49, 0, 0x18000
	v_add_u32_e32 v2, s49, v145
	s_add_i32 s50, 0, 0x1c000
	ds_read_b128 v[150:153], v2
	ds_read_b128 v[154:157], v2 offset:1024
	ds_read_b128 v[158:161], v2 offset:2048
	ds_read_b128 v[162:165], v2 offset:3072
	v_add_u32_e32 v2, s50, v145
	ds_read_b128 v[166:169], v2
	ds_read_b128 v[170:173], v2 offset:1024
	ds_read_b128 v[174:177], v2 offset:2048
	ds_read_b128 v[178:181], v2 offset:3072
	s_add_u32 s6, s20, 0x30000
	s_addc_u32 s7, s21, 0
	s_mov_b32 m0, s29
	v_lshl_add_u64 v[214:215], s[6:7], 0, v[138:139]
	ds_read_b128 v[182:185], v228 offset:32768
	ds_read_b128 v[186:189], v228 offset:33792
	ds_read_b128 v[190:193], v228 offset:34816
	ds_read_b128 v[194:197], v228 offset:35840
	ds_read_b128 v[198:201], v228 offset:36864
	ds_read_b128 v[202:205], v228 offset:37888
	ds_read_b128 v[206:209], v228 offset:38912
	ds_read_b128 v[210:213], v228 offset:39936
	global_load_lds_dwordx4 v[214:215], off
	v_lshl_add_u64 v[214:215], s[6:7], 0, v[134:135]
	s_mov_b32 m0, s30
	s_nop 0
	global_load_lds_dwordx4 v[214:215], off
	s_waitcnt vmcnt(8)
	s_waitcnt lgkmcnt(0)
	s_nop 0
	s_barrier
	s_setprio 1
	s_waitcnt lgkmcnt(0)
	v_mfma_f32_16x16x32_bf16 v[128:131], v[150:153], v[182:185], v[128:131]
	v_mfma_f32_16x16x32_bf16 v[124:127], v[158:161], v[182:185], v[124:127]
	v_mfma_f32_16x16x32_bf16 v[120:123], v[150:153], v[190:193], v[120:123]
	v_mfma_f32_16x16x32_bf16 v[116:119], v[158:161], v[190:193], v[116:119]
	v_mfma_f32_16x16x32_bf16 v[112:115], v[150:153], v[198:201], v[112:115]
	v_mfma_f32_16x16x32_bf16 v[108:111], v[158:161], v[198:201], v[108:111]
	v_mfma_f32_16x16x32_bf16 v[104:107], v[150:153], v[206:209], v[104:107]
	v_mfma_f32_16x16x32_bf16 v[100:103], v[158:161], v[206:209], v[100:103]
	v_mfma_f32_16x16x32_bf16 v[128:131], v[154:157], v[186:189], v[128:131]
	v_mfma_f32_16x16x32_bf16 v[124:127], v[162:165], v[186:189], v[124:127]
	v_mfma_f32_16x16x32_bf16 v[120:123], v[154:157], v[194:197], v[120:123]
	v_mfma_f32_16x16x32_bf16 v[116:119], v[162:165], v[194:197], v[116:119]
	v_mfma_f32_16x16x32_bf16 v[112:115], v[154:157], v[202:205], v[112:115]
	v_mfma_f32_16x16x32_bf16 v[108:111], v[162:165], v[202:205], v[108:111]
	v_mfma_f32_16x16x32_bf16 v[104:107], v[154:157], v[210:213], v[104:107]
	v_mfma_f32_16x16x32_bf16 v[100:103], v[162:165], v[210:213], v[100:103]
	s_setprio 0
	s_setprio 1
	v_mfma_f32_16x16x32_bf16 v[96:99], v[166:169], v[182:185], v[96:99]
	v_mfma_f32_16x16x32_bf16 v[92:95], v[174:177], v[182:185], v[92:95]
	v_mfma_f32_16x16x32_bf16 v[88:91], v[166:169], v[190:193], v[88:91]
	v_mfma_f32_16x16x32_bf16 v[84:87], v[174:177], v[190:193], v[84:87]
	v_mfma_f32_16x16x32_bf16 v[80:83], v[166:169], v[198:201], v[80:83]
	v_mfma_f32_16x16x32_bf16 v[76:79], v[174:177], v[198:201], v[76:79]
	v_mfma_f32_16x16x32_bf16 v[72:75], v[166:169], v[206:209], v[72:75]
	v_mfma_f32_16x16x32_bf16 v[68:71], v[174:177], v[206:209], v[68:71]
	v_mfma_f32_16x16x32_bf16 v[96:99], v[170:173], v[186:189], v[96:99]
	v_mfma_f32_16x16x32_bf16 v[92:95], v[178:181], v[186:189], v[92:95]
	v_mfma_f32_16x16x32_bf16 v[88:91], v[170:173], v[194:197], v[88:91]
	v_mfma_f32_16x16x32_bf16 v[84:87], v[178:181], v[194:197], v[84:87]
	v_mfma_f32_16x16x32_bf16 v[80:83], v[170:173], v[202:205], v[80:83]
	v_mfma_f32_16x16x32_bf16 v[76:79], v[178:181], v[202:205], v[76:79]
	v_mfma_f32_16x16x32_bf16 v[72:75], v[170:173], v[210:213], v[72:75]
	v_mfma_f32_16x16x32_bf16 v[68:71], v[178:181], v[210:213], v[68:71]
	s_setprio 0
	s_barrier
; #define PG8_WAIT_V(n) asm volatile("s_waitcnt vmcnt(" #n ")" ::: "memory")
; #define PG8_WAIT_L(n) asm volatile("s_waitcnt lgkmcnt(" #n ")" ::: "memory")
; #define PG8_BAR __builtin_amdgcn_s_barrier()
; #define PG8_SCHED __builtin_amdgcn_sched_barrier(0)
; template <class Epi, class Sched, bool ALIGN_EPI = false, bool SP2 = false, bool F8 = false>
; __device__ __forceinline__ void gemm_phase(PG8_LAS unsigned char* lds, const Gemm g, const Sched& S, const Epi& E) {
;     ...
;             PG8_LDB(B0, 0, 0); PG8_LDB(B1, 0, 1); PG8_SCHED; PG8_LDA(At, 0, 0); PG8_STAGE(PG8_SA(1, 1), a1 + hstep, voffA);
;             PG8_WAIT_V(8); PG8_WAIT_L(0); PG8_BAR; PG8_MMA(0, 0, At, B0); PG8_MMA(0, 1, At, B1); PG8_BAR; PG8_SCHED;
;             PG8_LDA(At, 0, 1); PG8_STAGE(PG8_SB(0, 0), b2, voffB); PG8_STAGE(PG8_SB(0, 1), b2 + hstep, voffB); PG8_STAGE(PG8_SA(0, 0), a2, voffA);
;             PG8_WAIT_V(8); PG8_WAIT_L(0); PG8_BAR; PG8_MMA(1, 0, At, B0); PG8_MMA(1, 1, At, B1); PG8_BAR; PG8_SCHED;
;             PG8_LDB(B0, 1, 0); PG8_LDB(B1, 1, 1); PG8_SCHED; PG8_LDA(At, 1, 0); PG8_STAGE(PG8_SA(0, 1), a2 + hstep, voffA);
;             PG8_WAIT_V(8); PG8_WAIT_L(0); PG8_BAR; PG8_MMA(0, 0, At, B0); PG8_MMA(0, 1, At, B1); PG8_BAR; PG8_SCHED;
;             PG8_LDA(At, 1, 1); PG8_STAGE(PG8_SB(1, 0), b3, voffB); PG8_STAGE(PG8_SB(1, 1), b3 + hstep, voffB); PG8_STAGE(PG8_SA(1, 0), a3, voffA);
;             PG8_WAIT_V(8); PG8_WAIT_L(0); PG8_BAR; PG8_MMA(1, 0, At, B0); PG8_MMA(1, 1, At, B1); PG8_BAR; PG8_SCHED;
	s_add_u32 s6, s18, 0x2000
	s_addc_u32 s7, s19, 0
	s_add_i32 s20, s49, s24
	v_lshl_add_u64 v[214:215], s[6:7], 0, v[136:137]
	s_mov_b32 m0, s20
	ds_read_b128 v[182:185], v228 offset:49152
	ds_read_b128 v[186:189], v228 offset:50176
	ds_read_b128 v[190:193], v228 offset:51200
	ds_read_b128 v[194:197], v228 offset:52224
	ds_read_b128 v[198:201], v228 offset:53248
	ds_read_b128 v[202:205], v228 offset:54272
	ds_read_b128 v[206:209], v228 offset:55296
	ds_read_b128 v[210:213], v228 offset:56320
	global_load_lds_dwordx4 v[214:215], off
	s_add_i32 m0, s20, 0x2000
	v_lshl_add_u64 v[214:215], s[6:7], 0, v[132:133]
	s_add_u32 s6, s18, 0x32000
	s_addc_u32 s7, s19, 0
	s_add_i32 s18, s50, s24
	global_load_lds_dwordx4 v[214:215], off
	v_lshl_add_u64 v[214:215], s[6:7], 0, v[136:137]
	s_mov_b32 m0, s18
	s_nop 0
	global_load_lds_dwordx4 v[214:215], off
	v_lshl_add_u64 v[214:215], s[6:7], 0, v[132:133]
	s_add_i32 m0, s18, 0x2000
	s_nop 0
	global_load_lds_dwordx4 v[214:215], off
	v_lshl_add_u64 v[214:215], s[16:17], 0, v[138:139]
	s_mov_b32 m0, s45
	s_nop 0
	global_load_lds_dwordx4 v[214:215], off
	v_lshl_add_u64 v[214:215], s[16:17], 0, v[134:135]
	s_mov_b32 m0, s52
	s_nop 0
	global_load_lds_dwordx4 v[214:215], off
	s_waitcnt vmcnt(8)
	s_waitcnt lgkmcnt(0)
	s_nop 0
	s_barrier
	s_setprio 1
	s_waitcnt lgkmcnt(0)
	v_mfma_f32_16x16x32_bf16 v[64:67], v[150:153], v[182:185], v[64:67]
	v_mfma_f32_16x16x32_bf16 v[60:63], v[158:161], v[182:185], v[60:63]
	v_mfma_f32_16x16x32_bf16 v[56:59], v[150:153], v[190:193], v[56:59]
	v_mfma_f32_16x16x32_bf16 v[52:55], v[158:161], v[190:193], v[52:55]
	v_mfma_f32_16x16x32_bf16 v[48:51], v[150:153], v[198:201], v[48:51]
	v_mfma_f32_16x16x32_bf16 v[44:47], v[158:161], v[198:201], v[44:47]
	v_mfma_f32_16x16x32_bf16 v[40:43], v[150:153], v[206:209], v[40:43]
	v_mfma_f32_16x16x32_bf16 v[36:39], v[158:161], v[206:209], v[36:39]
	v_mfma_f32_16x16x32_bf16 v[64:67], v[154:157], v[186:189], v[64:67]
	v_mfma_f32_16x16x32_bf16 v[60:63], v[162:165], v[186:189], v[60:63]
	v_mfma_f32_16x16x32_bf16 v[56:59], v[154:157], v[194:197], v[56:59]
	v_mfma_f32_16x16x32_bf16 v[52:55], v[162:165], v[194:197], v[52:55]
	v_mfma_f32_16x16x32_bf16 v[48:51], v[154:157], v[202:205], v[48:51]
	v_mfma_f32_16x16x32_bf16 v[44:47], v[162:165], v[202:205], v[44:47]
	v_mfma_f32_16x16x32_bf16 v[40:43], v[154:157], v[210:213], v[40:43]
	v_mfma_f32_16x16x32_bf16 v[36:39], v[162:165], v[210:213], v[36:39]
	s_setprio 0
	s_setprio 1
	v_mfma_f32_16x16x32_bf16 v[32:35], v[166:169], v[182:185], v[32:35]
	v_mfma_f32_16x16x32_bf16 v[28:31], v[174:177], v[182:185], v[28:31]
	v_mfma_f32_16x16x32_bf16 v[24:27], v[166:169], v[190:193], v[24:27]
	v_mfma_f32_16x16x32_bf16 v[20:23], v[174:177], v[190:193], v[20:23]
	v_mfma_f32_16x16x32_bf16 v[16:19], v[166:169], v[198:201], v[16:19]
	v_mfma_f32_16x16x32_bf16 v[12:15], v[174:177], v[198:201], v[12:15]
	v_mfma_f32_16x16x32_bf16 v[8:11], v[166:169], v[206:209], v[8:11]
	v_mfma_f32_16x16x32_bf16 v[4:7], v[174:177], v[206:209], v[4:7]
	v_mfma_f32_16x16x32_bf16 v[32:35], v[170:173], v[186:189], v[32:35]
	v_mfma_f32_16x16x32_bf16 v[28:31], v[178:181], v[186:189], v[28:31]
	v_mfma_f32_16x16x32_bf16 v[24:27], v[170:173], v[194:197], v[24:27]
	v_mfma_f32_16x16x32_bf16 v[20:23], v[178:181], v[194:197], v[20:23]
	v_mfma_f32_16x16x32_bf16 v[16:19], v[170:173], v[202:205], v[16:19]
	v_mfma_f32_16x16x32_bf16 v[12:15], v[178:181], v[202:205], v[12:15]
	v_mfma_f32_16x16x32_bf16 v[8:11], v[170:173], v[210:213], v[8:11]
	v_mfma_f32_16x16x32_bf16 v[4:7], v[178:181], v[210:213], v[4:7]
	s_setprio 0
	s_barrier
	s_add_i32 s48, s48, 2
	s_add_u32 s40, s40, 0x4000
	s_addc_u32 s41, s41, 0
	s_cmp_gt_u32 s48, 9
	s_mov_b64 s[6:7], s[14:15]
	s_cbranch_scc0 .LBB0_1314
	s_and_b64 vcc, exec, s[10:11]
	s_cbranch_vccz .LBB0_1317
	s_barrier

; #define PG8_WAIT_V(n) asm volatile("s_waitcnt vmcnt(" #n ")" ::: "memory")
; #define PG8_WAIT_L(n) asm volatile("s_waitcnt lgkmcnt(" #n ")" ::: "memory")
; #define PG8_BAR __builtin_amdgcn_s_barrier()
; #define PG8_SCHED __builtin_amdgcn_sched_barrier(0)
; template <class Epi, class Sched, bool ALIGN_EPI = false, bool SP2 = false, bool F8 = false>
; __device__ __forceinline__ void gemm_phase(PG8_LAS unsigned char* lds, const Gemm g, const Sched& S, const Epi& E) {
;     ...
;         for (int t = 0; t < nt; t += 2) {
;             const bool last = (t == nt - 2);
;             const char* a1 = cA + (size_t)(t + 1) * kstep;
;             const char* a2 = last ? nA : cA + (size_t)(t + 2) * kstep; const char* b2 = last ? nB : cB + (size_t)(t + 2) * kstep;
;             const char* a3 = a2 + kstep; const char* b3 = b2 + kstep;
;             if (last && has_next) S.a_ready(nxt);
;             if constexpr (SP2) {
;             PG8_LDB(B0, 0, 0); PG8_LDB(B1, 0, 1); PG8_SCHED; PG8_LDA(At, 0, 0); PG8_STAGE(PG8_SA(1, 1), a1 + hstep, voffA);
;             PG8_WAIT_V(8); PG8_WAIT_L(0); PG8_BAR; PG8_MMA(0, 0, At, B0); PG8_MMA(0, 1, At, B1); PG8_BAR; PG8_SCHED;
;             PG8_LDA(At, 0, 1); PG8_STAGE(PG8_SB(0, 0), b2, voffB); PG8_STAGE(PG8_SB(0, 1), b2 + hstep, voffB); PG8_STAGE(PG8_SA(0, 0), a2, voffA);
;             PG8_WAIT_V(8); PG8_WAIT_L(0); PG8_BAR; PG8_MMA(1, 0, At, B0); PG8_MMA(1, 1, At, B1); PG8_BAR; PG8_SCHED;
;             PG8_LDB(B0, 1, 0); PG8_LDB(B1, 1, 1); PG8_SCHED; PG8_LDA(At, 1, 0); PG8_STAGE(PG8_SA(0, 1), a2 + hstep, voffA);
;             PG8_WAIT_V(8); PG8_WAIT_L(0); PG8_BAR; PG8_MMA(0, 0, At, B0); PG8_MMA(0, 1, At, B1); PG8_BAR; PG8_SCHED;
;             PG8_LDA(At, 1, 1); PG8_STAGE(PG8_SB(1, 0), b3, voffB); PG8_STAGE(PG8_SB(1, 1), b3 + hstep, voffB); PG8_STAGE(PG8_SA(1, 0), a3, voffA);
;             PG8_WAIT_V(8); PG8_WAIT_L(0); PG8_BAR; PG8_MMA(1, 0, At, B0); PG8_MMA(1, 1, At, B1); PG8_BAR; PG8_SCHED;
.LBB0_1521:
	s_add_i32 s67, s28, 2
	s_add_u32 s29, s6, 0x2000
	s_addc_u32 s30, s7, 0
	s_cmp_eq_u32 s63, s28
	s_cselect_b32 s52, s0, s29
	s_cselect_b32 s53, s1, s30
	s_cselect_b32 s30, s22, s25
	s_cselect_b32 s31, s23, s65
	s_add_u32 s28, s52, 0x2000
	s_addc_u32 s29, s53, 0
	s_add_i32 s70, 0, 0x10000
	v_add_u32_e32 v2, s70, v203
	s_add_i32 s83, 0, 0x14000
	ds_read_b128 v[120:123], v2
	ds_read_b128 v[128:131], v2 offset:1024
	ds_read_b128 v[132:135], v2 offset:2048
	ds_read_b128 v[144:147], v2 offset:3072
	v_add_u32_e32 v2, s83, v203
	ds_read_b128 v[148:151], v2
	ds_read_b128 v[152:155], v2 offset:1024
	ds_read_b128 v[156:159], v2 offset:2048
	ds_read_b128 v[172:175], v2 offset:3072
	v_lshl_add_u64 v[214:215], s[6:7], 0, v[186:187]
	s_add_i32 m0, s48, 0xc000
	ds_read_b128 v[176:179], v204
	ds_read_b128 v[180:183], v204 offset:1024
	ds_read_b128 v[190:193], v204 offset:2048
	ds_read_b128 v[194:197], v204 offset:3072
	ds_read_b128 v[198:201], v204 offset:4096
	ds_read_b128 v[206:209], v204 offset:5120
	ds_read_b128 v[210:213], v204 offset:6144
	ds_read_b128 v[218:221], v204 offset:7168
	global_load_lds_dwordx4 v[214:215], off
	v_lshl_add_u64 v[214:215], s[6:7], 0, v[188:189]
	s_add_i32 m0, s48, 0xe000
	s_nop 0
	global_load_lds_dwordx4 v[214:215], off
	s_waitcnt vmcnt(8)
	s_waitcnt lgkmcnt(0)
	s_barrier
	s_setprio 1
	s_waitcnt lgkmcnt(0)
	v_mfma_f32_16x16x32_bf16 v[140:143], v[120:123], v[176:179], v[140:143]
	v_mfma_f32_16x16x32_bf16 v[136:139], v[132:135], v[176:179], v[136:139]
	v_mfma_f32_16x16x32_bf16 v[112:115], v[120:123], v[190:193], v[112:115]
	v_mfma_f32_16x16x32_bf16 v[108:111], v[132:135], v[190:193], v[108:111]
	v_mfma_f32_16x16x32_bf16 v[96:99], v[120:123], v[198:201], v[96:99]
	v_mfma_f32_16x16x32_bf16 v[92:95], v[132:135], v[198:201], v[92:95]
	v_mfma_f32_16x16x32_bf16 v[80:83], v[120:123], v[210:213], v[80:83]
	v_mfma_f32_16x16x32_bf16 v[76:79], v[132:135], v[210:213], v[76:79]
	v_mfma_f32_16x16x32_bf16 v[140:143], v[128:131], v[180:183], v[140:143]
	v_mfma_f32_16x16x32_bf16 v[136:139], v[144:147], v[180:183], v[136:139]
	v_mfma_f32_16x16x32_bf16 v[112:115], v[128:131], v[194:197], v[112:115]
	v_mfma_f32_16x16x32_bf16 v[108:111], v[144:147], v[194:197], v[108:111]
	v_mfma_f32_16x16x32_bf16 v[96:99], v[128:131], v[206:209], v[96:99]
	v_mfma_f32_16x16x32_bf16 v[92:95], v[144:147], v[206:209], v[92:95]
	v_mfma_f32_16x16x32_bf16 v[80:83], v[128:131], v[218:221], v[80:83]
	v_mfma_f32_16x16x32_bf16 v[76:79], v[144:147], v[218:221], v[76:79]
	s_setprio 0
	s_setprio 1
	v_mfma_f32_16x16x32_bf16 v[124:127], v[148:151], v[176:179], v[124:127]
	v_mfma_f32_16x16x32_bf16 v[116:119], v[156:159], v[176:179], v[116:119]
	v_mfma_f32_16x16x32_bf16 v[104:107], v[148:151], v[190:193], v[104:107]
	v_mfma_f32_16x16x32_bf16 v[100:103], v[156:159], v[190:193], v[100:103]
	v_mfma_f32_16x16x32_bf16 v[88:91], v[148:151], v[198:201], v[88:91]
	v_mfma_f32_16x16x32_bf16 v[84:87], v[156:159], v[198:201], v[84:87]
	v_mfma_f32_16x16x32_bf16 v[72:75], v[148:151], v[210:213], v[72:75]
	v_mfma_f32_16x16x32_bf16 v[68:71], v[156:159], v[210:213], v[68:71]
	v_mfma_f32_16x16x32_bf16 v[124:127], v[152:155], v[180:183], v[124:127]
	v_mfma_f32_16x16x32_bf16 v[116:119], v[172:175], v[180:183], v[116:119]
	v_mfma_f32_16x16x32_bf16 v[104:107], v[152:155], v[194:197], v[104:107]
	v_mfma_f32_16x16x32_bf16 v[100:103], v[172:175], v[194:197], v[100:103]
	v_mfma_f32_16x16x32_bf16 v[88:91], v[152:155], v[206:209], v[88:91]
	v_mfma_f32_16x16x32_bf16 v[84:87], v[172:175], v[206:209], v[84:87]
	v_mfma_f32_16x16x32_bf16 v[72:75], v[152:155], v[218:221], v[72:75]
	v_mfma_f32_16x16x32_bf16 v[68:71], v[172:175], v[218:221], v[68:71]
	s_setprio 0
	s_barrier
	s_add_i32 s70, s70, s45
	v_lshl_add_u64 v[214:215], s[30:31], 0, v[164:165]
	s_mov_b32 m0, s70
	ds_read_b128 v[176:179], v204 offset:16384
	ds_read_b128 v[180:183], v204 offset:17408
	ds_read_b128 v[190:193], v204 offset:18432
	ds_read_b128 v[194:197], v204 offset:19456
	ds_read_b128 v[198:201], v204 offset:20480
	ds_read_b128 v[206:209], v204 offset:21504
	ds_read_b128 v[210:213], v204 offset:22528
	ds_read_b128 v[218:221], v204 offset:23552
	global_load_lds_dwordx4 v[214:215], off
	s_add_i32 m0, s70, 0x2000
	s_add_u32 s70, s30, s34
	v_lshl_add_u64 v[214:215], s[30:31], 0, v[160:161]
	s_addc_u32 s71, s31, 0
	s_add_i32 s83, s83, s45
	global_load_lds_dwordx4 v[214:215], off
	v_lshl_add_u64 v[214:215], s[70:71], 0, v[164:165]
	s_mov_b32 m0, s83
	s_nop 0
	global_load_lds_dwordx4 v[214:215], off
	v_lshl_add_u64 v[214:215], s[70:71], 0, v[160:161]
	s_add_i32 m0, s83, 0x2000
	s_nop 0
	global_load_lds_dwordx4 v[214:215], off
	v_lshl_add_u64 v[214:215], s[52:53], 0, v[166:167]
	s_mov_b32 m0, s48
	s_nop 0
	global_load_lds_dwordx4 v[214:215], off
	v_lshl_add_u64 v[214:215], s[52:53], 0, v[162:163]
	s_mov_b32 m0, s49
	s_nop 0
	global_load_lds_dwordx4 v[214:215], off
	s_waitcnt vmcnt(8)
	s_waitcnt lgkmcnt(0)
	s_nop 0
	s_barrier
; #define PG8_WAIT_V(n) asm volatile("s_waitcnt vmcnt(" #n ")" ::: "memory")
; #define PG8_WAIT_L(n) asm volatile("s_waitcnt lgkmcnt(" #n ")" ::: "memory")
; #define PG8_BAR __builtin_amdgcn_s_barrier()
; #define PG8_SCHED __builtin_amdgcn_sched_barrier(0)
; template <class Epi, class Sched, bool ALIGN_EPI = false, bool SP2 = false, bool F8 = false>
; __device__ __forceinline__ void gemm_phase(PG8_LAS unsigned char* lds, const Gemm g, const Sched& S, const Epi& E) {
;     ...
;             PG8_LDB(B0, 0, 0); PG8_LDB(B1, 0, 1); PG8_SCHED; PG8_LDA(At, 0, 0); PG8_STAGE(PG8_SA(1, 1), a1 + hstep, voffA);
;             PG8_WAIT_V(8); PG8_WAIT_L(0); PG8_BAR; PG8_MMA(0, 0, At, B0); PG8_MMA(0, 1, At, B1); PG8_BAR; PG8_SCHED;
;             PG8_LDA(At, 0, 1); PG8_STAGE(PG8_SB(0, 0), b2, voffB); PG8_STAGE(PG8_SB(0, 1), b2 + hstep, voffB); PG8_STAGE(PG8_SA(0, 0), a2, voffA);
;             PG8_WAIT_V(8); PG8_WAIT_L(0); PG8_BAR; PG8_MMA(1, 0, At, B0); PG8_MMA(1, 1, At, B1); PG8_BAR; PG8_SCHED;
;             PG8_LDB(B0, 1, 0); PG8_LDB(B1, 1, 1); PG8_SCHED; PG8_LDA(At, 1, 0); PG8_STAGE(PG8_SA(0, 1), a2 + hstep, voffA);
;             PG8_WAIT_V(8); PG8_WAIT_L(0); PG8_BAR; PG8_MMA(0, 0, At, B0); PG8_MMA(0, 1, At, B1); PG8_BAR; PG8_SCHED;
;             PG8_LDA(At, 1, 1); PG8_STAGE(PG8_SB(1, 0), b3, voffB); PG8_STAGE(PG8_SB(1, 1), b3 + hstep, voffB); PG8_STAGE(PG8_SA(1, 0), a3, voffA);
;             PG8_WAIT_V(8); PG8_WAIT_L(0); PG8_BAR; PG8_MMA(1, 0, At, B0); PG8_MMA(1, 1, At, B1); PG8_BAR; PG8_SCHED;
	s_setprio 1
	s_waitcnt lgkmcnt(0)
	v_mfma_f32_16x16x32_bf16 v[64:67], v[120:123], v[176:179], v[64:67]
	v_mfma_f32_16x16x32_bf16 v[60:63], v[132:135], v[176:179], v[60:63]
	v_mfma_f32_16x16x32_bf16 v[48:51], v[120:123], v[190:193], v[48:51]
	v_mfma_f32_16x16x32_bf16 v[44:47], v[132:135], v[190:193], v[44:47]
	v_mfma_f32_16x16x32_bf16 v[32:35], v[120:123], v[198:201], v[32:35]
	v_mfma_f32_16x16x32_bf16 v[28:31], v[132:135], v[198:201], v[28:31]
	v_mfma_f32_16x16x32_bf16 v[16:19], v[120:123], v[210:213], v[16:19]
	v_mfma_f32_16x16x32_bf16 v[12:15], v[132:135], v[210:213], v[12:15]
	v_mfma_f32_16x16x32_bf16 v[64:67], v[128:131], v[180:183], v[64:67]
	v_mfma_f32_16x16x32_bf16 v[60:63], v[144:147], v[180:183], v[60:63]
	v_mfma_f32_16x16x32_bf16 v[48:51], v[128:131], v[194:197], v[48:51]
	v_mfma_f32_16x16x32_bf16 v[44:47], v[144:147], v[194:197], v[44:47]
	v_mfma_f32_16x16x32_bf16 v[32:35], v[128:131], v[206:209], v[32:35]
	v_mfma_f32_16x16x32_bf16 v[28:31], v[144:147], v[206:209], v[28:31]
	v_mfma_f32_16x16x32_bf16 v[16:19], v[128:131], v[218:221], v[16:19]
	v_mfma_f32_16x16x32_bf16 v[12:15], v[144:147], v[218:221], v[12:15]
	s_setprio 0
	s_setprio 1
	v_mfma_f32_16x16x32_bf16 v[56:59], v[148:151], v[176:179], v[56:59]
	v_mfma_f32_16x16x32_bf16 v[52:55], v[156:159], v[176:179], v[52:55]
	v_mfma_f32_16x16x32_bf16 v[40:43], v[148:151], v[190:193], v[40:43]
	v_mfma_f32_16x16x32_bf16 v[36:39], v[156:159], v[190:193], v[36:39]
	v_mfma_f32_16x16x32_bf16 v[24:27], v[148:151], v[198:201], v[24:27]
	v_mfma_f32_16x16x32_bf16 v[20:23], v[156:159], v[198:201], v[20:23]
	v_mfma_f32_16x16x32_bf16 v[8:11], v[148:151], v[210:213], v[8:11]
	v_mfma_f32_16x16x32_bf16 v[4:7], v[156:159], v[210:213], v[4:7]
	v_mfma_f32_16x16x32_bf16 v[56:59], v[152:155], v[180:183], v[56:59]
	v_mfma_f32_16x16x32_bf16 v[52:55], v[172:175], v[180:183], v[52:55]
	v_mfma_f32_16x16x32_bf16 v[40:43], v[152:155], v[194:197], v[40:43]
	v_mfma_f32_16x16x32_bf16 v[36:39], v[172:175], v[194:197], v[36:39]
	v_mfma_f32_16x16x32_bf16 v[24:27], v[152:155], v[206:209], v[24:27]
	v_mfma_f32_16x16x32_bf16 v[20:23], v[172:175], v[206:209], v[20:23]
	v_mfma_f32_16x16x32_bf16 v[8:11], v[152:155], v[218:221], v[8:11]
	v_mfma_f32_16x16x32_bf16 v[4:7], v[172:175], v[218:221], v[4:7]
	s_setprio 0
	s_barrier
	s_add_i32 s70, 0, 0x18000
	v_add_u32_e32 v2, s70, v203
	s_add_i32 s71, 0, 0x1c000
	ds_read_b128 v[120:123], v2
	ds_read_b128 v[128:131], v2 offset:1024
	ds_read_b128 v[132:135], v2 offset:2048
	ds_read_b128 v[144:147], v2 offset:3072
	v_add_u32_e32 v2, s71, v203
	ds_read_b128 v[148:151], v2
	ds_read_b128 v[152:155], v2 offset:1024
	ds_read_b128 v[156:159], v2 offset:2048
	ds_read_b128 v[172:175], v2 offset:3072
	s_add_u32 s52, s52, s34
	s_addc_u32 s53, s53, 0
	s_mov_b32 m0, s50
	v_lshl_add_u64 v[214:215], s[52:53], 0, v[166:167]
	ds_read_b128 v[176:179], v204 offset:32768
	ds_read_b128 v[180:183], v204 offset:33792
	ds_read_b128 v[190:193], v204 offset:34816
	ds_read_b128 v[194:197], v204 offset:35840
	ds_read_b128 v[198:201], v204 offset:36864
	ds_read_b128 v[206:209], v204 offset:37888
	ds_read_b128 v[210:213], v204 offset:38912
	ds_read_b128 v[218:221], v204 offset:39936
	global_load_lds_dwordx4 v[214:215], off
	v_lshl_add_u64 v[214:215], s[52:53], 0, v[162:163]
	s_mov_b32 m0, s54
	s_nop 0
	global_load_lds_dwordx4 v[214:215], off
	s_waitcnt vmcnt(8)
	s_waitcnt lgkmcnt(0)
	s_barrier
	s_setprio 1
	s_waitcnt lgkmcnt(0)
	v_mfma_f32_16x16x32_bf16 v[140:143], v[120:123], v[176:179], v[140:143]
	v_mfma_f32_16x16x32_bf16 v[136:139], v[132:135], v[176:179], v[136:139]
	v_mfma_f32_16x16x32_bf16 v[112:115], v[120:123], v[190:193], v[112:115]
	v_mfma_f32_16x16x32_bf16 v[108:111], v[132:135], v[190:193], v[108:111]
	v_mfma_f32_16x16x32_bf16 v[96:99], v[120:123], v[198:201], v[96:99]
	v_mfma_f32_16x16x32_bf16 v[92:95], v[132:135], v[198:201], v[92:95]
	v_mfma_f32_16x16x32_bf16 v[80:83], v[120:123], v[210:213], v[80:83]
	v_mfma_f32_16x16x32_bf16 v[76:79], v[132:135], v[210:213], v[76:79]
	v_mfma_f32_16x16x32_bf16 v[140:143], v[128:131], v[180:183], v[140:143]
	v_mfma_f32_16x16x32_bf16 v[136:139], v[144:147], v[180:183], v[136:139]
	v_mfma_f32_16x16x32_bf16 v[112:115], v[128:131], v[194:197], v[112:115]
	v_mfma_f32_16x16x32_bf16 v[108:111], v[144:147], v[194:197], v[108:111]
	v_mfma_f32_16x16x32_bf16 v[96:99], v[128:131], v[206:209], v[96:99]
	v_mfma_f32_16x16x32_bf16 v[92:95], v[144:147], v[206:209], v[92:95]
	v_mfma_f32_16x16x32_bf16 v[80:83], v[128:131], v[218:221], v[80:83]
	v_mfma_f32_16x16x32_bf16 v[76:79], v[144:147], v[218:221], v[76:79]
	s_setprio 0
	s_setprio 1
	v_mfma_f32_16x16x32_bf16 v[124:127], v[148:151], v[176:179], v[124:127]
	v_mfma_f32_16x16x32_bf16 v[116:119], v[156:159], v[176:179], v[116:119]
	v_mfma_f32_16x16x32_bf16 v[104:107], v[148:151], v[190:193], v[104:107]
	v_mfma_f32_16x16x32_bf16 v[100:103], v[156:159], v[190:193], v[100:103]
	v_mfma_f32_16x16x32_bf16 v[88:91], v[148:151], v[198:201], v[88:91]
	v_mfma_f32_16x16x32_bf16 v[84:87], v[156:159], v[198:201], v[84:87]
	v_mfma_f32_16x16x32_bf16 v[72:75], v[148:151], v[210:213], v[72:75]
	v_mfma_f32_16x16x32_bf16 v[68:71], v[156:159], v[210:213], v[68:71]
	v_mfma_f32_16x16x32_bf16 v[124:127], v[152:155], v[180:183], v[124:127]
	v_mfma_f32_16x16x32_bf16 v[116:119], v[172:175], v[180:183], v[116:119]
	v_mfma_f32_16x16x32_bf16 v[104:107], v[152:155], v[194:197], v[104:107]
	v_mfma_f32_16x16x32_bf16 v[100:103], v[172:175], v[194:197], v[100:103]
	v_mfma_f32_16x16x32_bf16 v[88:91], v[152:155], v[206:209], v[88:91]
	v_mfma_f32_16x16x32_bf16 v[84:87], v[172:175], v[206:209], v[84:87]
	v_mfma_f32_16x16x32_bf16 v[72:75], v[152:155], v[218:221], v[72:75]
	v_mfma_f32_16x16x32_bf16 v[68:71], v[172:175], v[218:221], v[68:71]
	s_setprio 0
	s_barrier
; #define PG8_WAIT_V(n) asm volatile("s_waitcnt vmcnt(" #n ")" ::: "memory")
; #define PG8_WAIT_L(n) asm volatile("s_waitcnt lgkmcnt(" #n ")" ::: "memory")
; #define PG8_BAR __builtin_amdgcn_s_barrier()
; #define PG8_SCHED __builtin_amdgcn_sched_barrier(0)
; template <class Epi, class Sched, bool ALIGN_EPI = false, bool SP2 = false, bool F8 = false>
; __device__ __forceinline__ void gemm_phase(PG8_LAS unsigned char* lds, const Gemm g, const Sched& S, const Epi& E) {
;     ...
;             PG8_LDB(B0, 0, 0); PG8_LDB(B1, 0, 1); PG8_SCHED; PG8_LDA(At, 0, 0); PG8_STAGE(PG8_SA(1, 1), a1 + hstep, voffA);
;             PG8_WAIT_V(8); PG8_WAIT_L(0); PG8_BAR; PG8_MMA(0, 0, At, B0); PG8_MMA(0, 1, At, B1); PG8_BAR; PG8_SCHED;
;             PG8_LDA(At, 0, 1); PG8_STAGE(PG8_SB(0, 0), b2, voffB); PG8_STAGE(PG8_SB(0, 1), b2 + hstep, voffB); PG8_STAGE(PG8_SA(0, 0), a2, voffA);
;             PG8_WAIT_V(8); PG8_WAIT_L(0); PG8_BAR; PG8_MMA(1, 0, At, B0); PG8_MMA(1, 1, At, B1); PG8_BAR; PG8_SCHED;
;             PG8_LDB(B0, 1, 0); PG8_LDB(B1, 1, 1); PG8_SCHED; PG8_LDA(At, 1, 0); PG8_STAGE(PG8_SA(0, 1), a2 + hstep, voffA);
;             PG8_WAIT_V(8); PG8_WAIT_L(0); PG8_BAR; PG8_MMA(0, 0, At, B0); PG8_MMA(0, 1, At, B1); PG8_BAR; PG8_SCHED;
;             PG8_LDA(At, 1, 1); PG8_STAGE(PG8_SB(1, 0), b3, voffB); PG8_STAGE(PG8_SB(1, 1), b3 + hstep, voffB); PG8_STAGE(PG8_SA(1, 0), a3, voffA);
;             PG8_WAIT_V(8); PG8_WAIT_L(0); PG8_BAR; PG8_MMA(1, 0, At, B0); PG8_MMA(1, 1, At, B1); PG8_BAR; PG8_SCHED;
	s_add_u32 s30, s30, 0x2000
	s_addc_u32 s31, s31, 0
	s_add_i32 s52, s70, s45
	v_lshl_add_u64 v[214:215], s[30:31], 0, v[164:165]
	s_mov_b32 m0, s52
	ds_read_b128 v[176:179], v204 offset:49152
	ds_read_b128 v[180:183], v204 offset:50176
	ds_read_b128 v[190:193], v204 offset:51200
	ds_read_b128 v[194:197], v204 offset:52224
	ds_read_b128 v[198:201], v204 offset:53248
	ds_read_b128 v[206:209], v204 offset:54272
	ds_read_b128 v[210:213], v204 offset:55296
	ds_read_b128 v[218:221], v204 offset:56320
	global_load_lds_dwordx4 v[214:215], off
	s_add_i32 m0, s52, 0x2000
	v_lshl_add_u64 v[214:215], s[30:31], 0, v[160:161]
	s_add_u32 s30, s30, s34
	s_addc_u32 s31, s31, 0
	s_add_i32 s52, s71, s45
	global_load_lds_dwordx4 v[214:215], off
	v_lshl_add_u64 v[214:215], s[30:31], 0, v[164:165]
	s_mov_b32 m0, s52
	s_nop 0
	global_load_lds_dwordx4 v[214:215], off
	v_lshl_add_u64 v[214:215], s[30:31], 0, v[160:161]
	s_add_i32 m0, s52, 0x2000
	s_nop 0
	global_load_lds_dwordx4 v[214:215], off
	v_lshl_add_u64 v[214:215], s[28:29], 0, v[166:167]
	s_mov_b32 m0, s61
	s_nop 0
	global_load_lds_dwordx4 v[214:215], off
	v_lshl_add_u64 v[214:215], s[28:29], 0, v[162:163]
	s_mov_b32 m0, s62
	s_nop 0
	global_load_lds_dwordx4 v[214:215], off
	s_waitcnt vmcnt(8)
	s_waitcnt lgkmcnt(0)
	s_barrier
	s_setprio 1
	s_waitcnt lgkmcnt(0)
	v_mfma_f32_16x16x32_bf16 v[64:67], v[120:123], v[176:179], v[64:67]
	v_mfma_f32_16x16x32_bf16 v[60:63], v[132:135], v[176:179], v[60:63]
	v_mfma_f32_16x16x32_bf16 v[48:51], v[120:123], v[190:193], v[48:51]
	v_mfma_f32_16x16x32_bf16 v[44:47], v[132:135], v[190:193], v[44:47]
	v_mfma_f32_16x16x32_bf16 v[32:35], v[120:123], v[198:201], v[32:35]
	v_mfma_f32_16x16x32_bf16 v[28:31], v[132:135], v[198:201], v[28:31]
	v_mfma_f32_16x16x32_bf16 v[16:19], v[120:123], v[210:213], v[16:19]
	v_mfma_f32_16x16x32_bf16 v[12:15], v[132:135], v[210:213], v[12:15]
	v_mfma_f32_16x16x32_bf16 v[64:67], v[128:131], v[180:183], v[64:67]
	v_mfma_f32_16x16x32_bf16 v[60:63], v[144:147], v[180:183], v[60:63]
	v_mfma_f32_16x16x32_bf16 v[48:51], v[128:131], v[194:197], v[48:51]
	v_mfma_f32_16x16x32_bf16 v[44:47], v[144:147], v[194:197], v[44:47]
	v_mfma_f32_16x16x32_bf16 v[32:35], v[128:131], v[206:209], v[32:35]
	v_mfma_f32_16x16x32_bf16 v[28:31], v[144:147], v[206:209], v[28:31]
	v_mfma_f32_16x16x32_bf16 v[16:19], v[128:131], v[218:221], v[16:19]
	v_mfma_f32_16x16x32_bf16 v[12:15], v[144:147], v[218:221], v[12:15]
	s_setprio 0
	s_setprio 1
	v_mfma_f32_16x16x32_bf16 v[56:59], v[148:151], v[176:179], v[56:59]
	v_mfma_f32_16x16x32_bf16 v[52:55], v[156:159], v[176:179], v[52:55]
	v_mfma_f32_16x16x32_bf16 v[40:43], v[148:151], v[190:193], v[40:43]
	v_mfma_f32_16x16x32_bf16 v[36:39], v[156:159], v[190:193], v[36:39]
	v_mfma_f32_16x16x32_bf16 v[24:27], v[148:151], v[198:201], v[24:27]
	v_mfma_f32_16x16x32_bf16 v[20:23], v[156:159], v[198:201], v[20:23]
	v_mfma_f32_16x16x32_bf16 v[8:11], v[148:151], v[210:213], v[8:11]
	v_mfma_f32_16x16x32_bf16 v[4:7], v[156:159], v[210:213], v[4:7]
	v_mfma_f32_16x16x32_bf16 v[56:59], v[152:155], v[180:183], v[56:59]
	v_mfma_f32_16x16x32_bf16 v[52:55], v[172:175], v[180:183], v[52:55]
	v_mfma_f32_16x16x32_bf16 v[40:43], v[152:155], v[194:197], v[40:43]
	v_mfma_f32_16x16x32_bf16 v[36:39], v[172:175], v[194:197], v[36:39]
	v_mfma_f32_16x16x32_bf16 v[24:27], v[152:155], v[206:209], v[24:27]
	v_mfma_f32_16x16x32_bf16 v[20:23], v[172:175], v[206:209], v[20:23]
	v_mfma_f32_16x16x32_bf16 v[8:11], v[152:155], v[218:221], v[8:11]
	v_mfma_f32_16x16x32_bf16 v[4:7], v[172:175], v[218:221], v[4:7]
	s_setprio 0
	s_barrier
	s_add_u32 s6, s6, 0x4000
	s_addc_u32 s7, s7, 0
	s_add_u32 s25, s25, 0x4000
	s_addc_u32 s65, s65, 0
	s_cmp_ge_u32 s67, s55
	s_mov_b32 s28, s67
	s_cbranch_scc0 .LBB0_1521
	s_and_b64 vcc, exec, s[20:21]
	s_cbranch_vccz .LBB0_1524
	s_barrier
